# attention K/V staging pipelined: next tile's LDS writes issued after this tile's QK MFMAs, refill loads at exp-block start; tile start is lgkmcnt(0)+barrier only
# speedup vs baseline: 1.0025x; 1.0006x over previous
; DI int TIDX() { int t = threadIdx.x; asm volatile("" : "+v"(t)); return t; }
; template <int DK, bool MLA>
; DI void attn_item(const h16* __restrict__ Q, const h16* __restrict__ Kp, const h16* __restrict__ Kr, const h16* __restrict__ Vt,
;                   int kbeg, int kend, h16* __restrict__ out, h16* sm) {
;     ...
;   const int tid = TIDX(), lane = tid & 63, w = tid >> 6, r = lane & 31, hh = lane >> 5;
;   h16x8 qf[DK / 16];
;   {
;     const h16* qr = Q + (size_t)(w * 32 + r) * DK + hh * 8;
; #pragma unroll
;     for (int ks = 0; ks < DK / 16; ++ks) qf[ks] = *(const h16x8*)(qr + ks * 16);
;   }
;   f32x16 ot[2];
; #pragma unroll
;   for (int i = 0; i < 16; ++i) { ot[0][i] = 0.f; ot[1][i] = 0.f; }
;   float m = -1000.f, lsum = 0.f;
;   u32x4 rkA[NCH], rvA[2], rkB[NCH], rvB[2];
;     ...
;   const int ntile = (kend - kbeg) >> 6;
;   ATT_GLOAD(rkA, rvA, kbeg)
;   ATT_GLOAD(rkB, rvB, kbeg + 64)
;   auto tile = [&](int it, u32x4 (&RK)[NCH], u32x4 (&RV)[2]) {
;     h16* ksm = sm + (it & 1) * BUF;
;     h16* vsm = ksm + 64 * KS;
; #pragma unroll
;     for (int i = 0; i < NCH; ++i) {
;       const int c = tid + 256 * i, key = c / NKC, part = c % NKC;
;       *(u32x4*)(ksm + key * KS + part * 8) = RK[i];
;     }
; #pragma unroll
;     for (int i = 0; i < 2; ++i) {
;       const int c = tid + 256 * i, dv = c >> 3, kc = c & 7;
;       *(u32x4*)(vsm + dv * 72 + kc * 8) = RV[i];
;     }
;     __syncthreads();
;     if (it + 2 < ntile) ATT_GLOAD(RK, RV, kbeg + (it + 2) * 64)
.LBB0_2732:
	s_and_b32 s53, s27, 7
	s_or_b32 s11, s53, s13
	s_mov_b64 s[8:9], -1
	s_andn2_b64 vcc, exec, s[6:7]
	s_mul_i32 s27, s11, 0x1100
	s_cbranch_vccz .LBB0_2744
	v_mov_b32_e32 v12, v203
	s_add_i32 s6, s27, s10
	s_mov_b32 s7, s37
	s_movk_i32 s2, 0xffe0
	v_ashrrev_i32_e32 v0, 1, v12
	s_lshl_b64 s[6:7], s[6:7], 7
	s_waitcnt vmcnt(4)
	v_bfi_b32 v144, s2, v0, v12
	s_add_u32 s8, s21, s6
	s_waitcnt vmcnt(2)
	v_ashrrev_i32_e32 v145, 31, v144
	s_addc_u32 s9, s22, s7
	v_bfe_u32 v13, v12, 5, 1
	v_lshlrev_b64 v[2:3], 7, v[144:145]
	v_lshl_add_u64 v[2:3], s[8:9], 0, v[2:3]
	v_lshlrev_b32_e32 v0, 4, v13
	s_lshr_b32 s6, s53, 2
	v_lshl_add_u64 v[2:3], v[2:3], 0, v[0:1]
	s_or_b32 s6, s6, s14
	global_load_dwordx4 v[80:83], v[2:3], off
	global_load_dwordx4 v[84:87], v[2:3], off offset:32
	global_load_dwordx4 v[88:91], v[2:3], off offset:64
	global_load_dwordx4 v[92:95], v[2:3], off offset:96
	v_ashrrev_i32_e32 v2, 31, v12
	s_mul_i32 s38, s6, 0x88000
	v_lshrrev_b32_e32 v2, 29, v2
	v_add_u32_e32 v10, 0x100, v12
	s_add_u32 s6, s23, s38
	v_add_u32_e32 v8, v12, v2
	v_ashrrev_i32_e32 v2, 31, v10
	s_addc_u32 s7, s24, 0
	v_lshrrev_b32_e32 v2, 29, v2
	s_add_u32 s38, s25, s38
	v_add_u32_e32 v4, v10, v2
	s_addc_u32 s39, s48, 0
	v_ashrrev_i32_e32 v15, 3, v4
	s_or_b32 s9, s26, 64
	v_and_b32_e32 v4, -8, v4
	v_ashrrev_i32_e32 v14, 3, v8
	v_add_u32_e32 v2, s9, v15
	v_sub_u32_e32 v16, v10, v4
	v_and_b32_e32 v8, -8, v8
	s_sub_i32 s8, 0x1100, s26
	v_ashrrev_i32_e32 v3, 31, v2
	v_lshlrev_b32_e32 v4, 3, v16
	v_add_u32_e32 v6, s9, v14
	v_sub_u32_e32 v17, v12, v8
	s_lshr_b32 s8, s8, 6
	v_lshlrev_b64 v[2:3], 7, v[2:3]
	v_ashrrev_i32_e32 v5, 31, v4
	v_ashrrev_i32_e32 v7, 31, v6
	v_lshlrev_b32_e32 v8, 3, v17
	s_lshl_b32 s9, s26, 1
	v_lshl_add_u64 v[2:3], s[6:7], 0, v[2:3]
	v_lshlrev_b64 v[4:5], 1, v[4:5]
	v_lshlrev_b64 v[6:7], 7, v[6:7]
	v_ashrrev_i32_e32 v9, 31, v8
	s_add_u32 s38, s38, s9
	v_lshl_add_u64 v[2:3], v[2:3], 0, v[4:5]
	v_lshl_add_u64 v[6:7], s[6:7], 0, v[6:7]
	v_lshlrev_b64 v[8:9], 1, v[8:9]
	s_addc_u32 s39, s39, 0
	v_lshl_add_u64 v[6:7], v[6:7], 0, v[8:9]
	global_load_dwordx4 v[96:99], v[2:3], off
	global_load_dwordx4 v[100:103], v[6:7], off
	v_ashrrev_i32_e32 v18, 3, v10
	v_mov_b64_e32 v[2:3], s[38:39]
	s_movk_i32 s2, 0x2200
	v_lshlrev_b32_e32 v10, 4, v12
	v_ashrrev_i32_e32 v19, 3, v12
	v_add_u32_e32 v130, s26, v15
	v_mad_i64_i32 v[6:7], s[40:41], v18, s2, v[2:3]
	v_and_b32_e32 v10, 0x70, v10
	v_mov_b32_e32 v11, v1
	v_mad_i64_i32 v[2:3], s[40:41], v19, s2, v[2:3]
	v_add_u32_e32 v128, s26, v14
	v_lshl_add_u64 v[134:135], v[2:3], 0, v[10:11]
	v_lshl_add_u64 v[2:3], s[38:39], 0, v[10:11]
	v_ashrrev_i32_e32 v131, 31, v130
	v_mad_i64_i32 v[136:137], s[38:39], v18, s2, v[2:3]
	v_mad_i64_i32 v[138:139], s[38:39], v19, s2, v[2:3]
	v_lshlrev_b64 v[2:3], 7, v[130:131]
	v_ashrrev_i32_e32 v129, 31, v128
	v_lshl_add_u64 v[132:133], v[6:7], 0, v[10:11]
	v_lshl_add_u64 v[2:3], s[6:7], 0, v[2:3]
	v_lshlrev_b64 v[6:7], 7, v[128:129]
	v_lshl_add_u64 v[2:3], v[2:3], 0, v[4:5]
	v_lshl_add_u64 v[6:7], s[6:7], 0, v[6:7]
	global_load_dwordx4 v[104:107], v[132:133], off offset:128
	global_load_dwordx4 v[108:111], v[134:135], off offset:128
	global_load_dwordx4 v[112:115], v[136:137], off
	global_load_dwordx4 v[116:119], v[138:139], off
	v_lshl_add_u64 v[6:7], v[6:7], 0, v[8:9]
	global_load_dwordx4 v[120:123], v[2:3], off
	global_load_dwordx4 v[124:127], v[6:7], off
	v_and_b32_e32 v2, 31, v12
	v_mul_lo_u32 v3, v14, s28
	v_mul_u32_u24_e32 v2, 0x48, v2
	v_lshl_add_u32 v129, v17, 4, v3
	v_mul_lo_u32 v3, v15, s28
	v_mad_u64_u32 v[140:141], s[38:39], v19, s28, v[10:11]
	v_mad_u64_u32 v[142:143], s[38:39], v18, s28, v[10:11]
	v_lshlrev_b32_e32 v2, 1, v2
	v_mov_b32_e32 v14, v1
	v_mov_b32_e32 v15, v1
	v_lshl_add_u32 v131, v16, 4, v3
	v_lshl_add_u64 v[148:149], s[6:7], 0, v[8:9]
	v_lshl_add_u64 v[150:151], s[6:7], 0, v[4:5]
	v_add_u32_e32 v141, v2, v0
	s_waitcnt vmcnt(13)
	v_lshlrev_b32_e32 v146, 2, v13
	v_lshl_add_u32 v143, v13, 4, v2
	v_mov_b32_e32 v0, v1
	v_mov_b32_e32 v2, v1
	v_mov_b32_e32 v3, v1
	v_mov_b32_e32 v4, v1
	v_mov_b32_e32 v5, v1
	v_mov_b32_e32 v6, v1
	v_mov_b32_e32 v7, v1
	v_mov_b32_e32 v8, v1
	v_mov_b32_e32 v9, v1
	v_mov_b32_e32 v10, v1
	v_mov_b32_e32 v12, v1
	v_mov_b32_e32 v13, v1
	v_mov_b64_e32 v[30:31], v[14:15]
	v_mov_b64_e32 v[46:47], v[14:15]
	s_mov_b32 s9, 3
	s_waitcnt vmcnt(12)
	v_mov_b32_e32 v147, 0xc47a0000
	v_mov_b32_e32 v153, 0
	s_movk_i32 s6, 0xc0
	v_mov_b64_e32 v[28:29], v[12:13]
	v_mov_b64_e32 v[26:27], v[10:11]
	v_mov_b64_e32 v[24:25], v[8:9]
	v_mov_b64_e32 v[22:23], v[6:7]
	v_mov_b64_e32 v[20:21], v[4:5]
	v_mov_b64_e32 v[18:19], v[2:3]
	v_mov_b64_e32 v[16:17], v[0:1]
	v_mov_b64_e32 v[44:45], v[12:13]
	v_mov_b64_e32 v[42:43], v[10:11]
	v_mov_b64_e32 v[40:41], v[8:9]
	v_mov_b64_e32 v[38:39], v[6:7]
	v_mov_b64_e32 v[36:37], v[4:5]
	v_mov_b64_e32 v[34:35], v[2:3]
	v_mov_b64_e32 v[32:33], v[0:1]
	v_mov_b32_e32 v204, 0x447a0000
	v_mov_b32_e32 v205, 0x447a0000
	v_mov_b32_e32 v206, 0x447a0000
	v_mov_b32_e32 v207, 0x447a0000
	v_mov_b32_e32 v208, 0x447a0000
	v_mov_b32_e32 v209, 0x447a0000
	v_mov_b32_e32 v210, 0x447a0000
	v_mov_b32_e32 v211, 0x447a0000
	v_mov_b32_e32 v212, 0x447a0000
	v_mov_b32_e32 v213, 0x447a0000
	v_mov_b32_e32 v214, 0x447a0000
	v_mov_b32_e32 v215, 0x447a0000
	v_mov_b32_e32 v216, 0x447a0000
	v_mov_b32_e32 v217, 0x447a0000
	v_mov_b32_e32 v218, 0x447a0000
	v_mov_b32_e32 v219, 0x447a0000
	s_movk_i32 s40, 0x80
	v_add_u32_e32 v2, s40, v128
	v_ashrrev_i32_e32 v3, 31, v2
	v_add_u32_e32 v4, s40, v130
	v_lshlrev_b64 v[2:3], 7, v[2:3]
	v_ashrrev_i32_e32 v5, 31, v4
	v_lshl_add_u64 v[220:221], v[148:149], 0, v[2:3]
	v_lshlrev_b64 v[4:5], 7, v[4:5]
	v_lshl_add_u64 v[222:223], v[150:151], 0, v[4:5]
	v_mov_b32_e32 v228, 0x2000
	v_mov_b32_e32 v229, 0
	s_waitcnt vmcnt(0)
	ds_write_b128 v129, v[124:127]
	ds_write_b128 v131, v[120:123]
	ds_write_b128 v140, v[116:119] offset:9216
	ds_write_b128 v142, v[112:115] offset:9216
	s_add_i32 s38, s9, -1
	s_cmp_ge_u32 s38, s8
	s_cbranch_scc1 .Lga_e_done
	s_waitcnt lgkmcnt(0)
	s_sub_i32 s40, s6, 64
	s_ashr_i32 s41, s40, 31
	s_lshl_b64 s[40:41], s[40:41], 1
	global_load_dwordx4 v[124:127], v[220:221], off
	global_load_dwordx4 v[120:123], v[222:223], off
	v_lshl_add_u64 v[2:3], v[138:139], 0, s[40:41]
	v_lshl_add_u64 v[4:5], v[136:137], 0, s[40:41]
	global_load_dwordx4 v[116:119], v[2:3], off
	global_load_dwordx4 v[112:115], v[4:5], off
	v_lshl_add_u64 v[220:221], v[220:221], 0, v[228:229]
	v_lshl_add_u64 v[222:223], v[222:223], 0, v[228:229]
; template <int DK, bool MLA>
; DI void attn_item(const h16* __restrict__ Q, const h16* __restrict__ Kp, const h16* __restrict__ Kr, const h16* __restrict__ Vt,
;                   int kbeg, int kend, h16* __restrict__ out, h16* sm) {
;     ...
;   const int ntile = (kend - kbeg) >> 6;
;   ATT_GLOAD(rkA, rvA, kbeg)
;   ATT_GLOAD(rkB, rvB, kbeg + 64)
;   auto tile = [&](int it, u32x4 (&RK)[NCH], u32x4 (&RV)[2]) {
;     h16* ksm = sm + (it & 1) * BUF;
;     h16* vsm = ksm + 64 * KS;
; #pragma unroll
;     for (int i = 0; i < NCH; ++i) {
;       const int c = tid + 256 * i, key = c / NKC, part = c % NKC;
;       *(u32x4*)(ksm + key * KS + part * 8) = RK[i];
;     }
; #pragma unroll
;     for (int i = 0; i < 2; ++i) {
;       const int c = tid + 256 * i, dv = c >> 3, kc = c & 7;
;       *(u32x4*)(vsm + dv * 72 + kc * 8) = RV[i];
;     }
;     __syncthreads();
;     if (it + 2 < ntile) ATT_GLOAD(RK, RV, kbeg + (it + 2) * 64)
.Lga_e_done:
	s_branch .LBB0_2735
.LBB0_2734:
	s_add_i32 s40, s9, 1
	s_cmp_ge_u32 s40, s8
	s_cbranch_scc1 .Lga_b2_done
	s_waitcnt lgkmcnt(0)
	s_add_i32 s40, s6, 64
	s_ashr_i32 s41, s40, 31
	s_lshl_b64 s[40:41], s[40:41], 1
	global_load_dwordx4 v[124:127], v[220:221], off
	global_load_dwordx4 v[120:123], v[222:223], off
	v_lshl_add_u64 v[2:3], v[138:139], 0, s[40:41]
	v_lshl_add_u64 v[4:5], v[136:137], 0, s[40:41]
	global_load_dwordx4 v[116:119], v[2:3], off
	global_load_dwordx4 v[112:115], v[4:5], off
	v_lshl_add_u64 v[220:221], v[220:221], 0, v[228:229]
	v_lshl_add_u64 v[222:223], v[222:223], 0, v[228:229]

; #define MFMA(a, b, c) __builtin_amdgcn_mfma_f32_32x32x16_f16((a), (b), (c), 0, 0, 0)
; template <int DK, bool MLA>
; DI void attn_item(const h16* __restrict__ Q, const h16* __restrict__ Kp, const h16* __restrict__ Kr, const h16* __restrict__ Vt,
;                   int kbeg, int kend, h16* __restrict__ out, h16* sm) {
;     ...
; #pragma unroll
;     for (int i = 0; i < NCH; ++i) {
;       const int c = tid + 256 * i, key = c / NKC, part = c % NKC;
;       *(u32x4*)(ksm + key * KS + part * 8) = RK[i];
;     }
; #pragma unroll
;     for (int i = 0; i < 2; ++i) {
;       const int c = tid + 256 * i, dv = c >> 3, kc = c & 7;
;       *(u32x4*)(vsm + dv * 72 + kc * 8) = RV[i];
;     }
;     __syncthreads();
;     if (it + 2 < ntile) ATT_GLOAD(RK, RV, kbeg + (it + 2) * 64)
;     f32x16 st[2];
;     const float negm = -m;
; #pragma unroll
;     for (int i = 0; i < 16; ++i) { st[0][i] = negm; st[1][i] = negm; }
; #pragma unroll
;     for (int ks = 0; ks < DK / 16; ++ks) {
;       h16x8 k0 = *(const h16x8*)(ksm + r * KS + ks * 16 + hh * 8);
;       h16x8 k1 = *(const h16x8*)(ksm + (32 + r) * KS + ks * 16 + hh * 8);
;       st[0] = MFMA(k0, qf[ks], st[0]);
;       st[1] = MFMA(k1, qf[ks], st[1]);
;     }
;     float mx = fmaxf(st[0][0], st[1][0]);
; #pragma unroll
;     for (int i = 1; i < 16; ++i) mx = fmaxf(mx, fmaxf(st[0][i], st[1][i]));
;     mx = x32_max(mx);
;     if (__builtin_amdgcn_ballot_w64(mx > 8.f) != 0) {
;       const float dlt = fmaxf(mx, 0.f);
;       const float alpha = __builtin_amdgcn_exp2f(-dlt);
;       m += dlt;
;       lsum *= alpha;
; #pragma unroll
;       for (int i = 0; i < 16; ++i) { ot[0][i] *= alpha; ot[1][i] *= alpha; st[0][i] -= dlt; st[1][i] -= dlt; }
;     }
.LBB0_2735:
	s_add_i32 s38, s9, -1
	s_cmp_ge_u32 s38, s8
	s_waitcnt lgkmcnt(0)
	s_barrier
.LBB0_2737:
	ds_read_b128 v[2:5], v141
	s_waitcnt lgkmcnt(0)
	s_nop 0
	v_mfma_f32_32x32x16_f16 v[64:79], v[2:5], v[80:83], v[204:219]
	ds_read_b128 v[2:5], v141 offset:4608
	s_waitcnt lgkmcnt(0)
	v_mfma_f32_32x32x16_f16 v[48:63], v[2:5], v[80:83], v[204:219]
	ds_read_b128 v[2:5], v141 offset:32
	s_waitcnt lgkmcnt(0)
	v_mfma_f32_32x32x16_f16 v[64:79], v[2:5], v[84:87], v[64:79]
	ds_read_b128 v[2:5], v141 offset:4640
	s_waitcnt lgkmcnt(0)
	v_mfma_f32_32x32x16_f16 v[48:63], v[2:5], v[84:87], v[48:63]
	ds_read_b128 v[2:5], v141 offset:64
	s_waitcnt lgkmcnt(0)
	v_mfma_f32_32x32x16_f16 v[64:79], v[2:5], v[88:91], v[64:79]
	ds_read_b128 v[2:5], v141 offset:4672
	s_waitcnt lgkmcnt(0)
	v_mfma_f32_32x32x16_f16 v[48:63], v[2:5], v[88:91], v[48:63]
	ds_read_b128 v[2:5], v141 offset:4704
	s_waitcnt lgkmcnt(0)
	v_mfma_f32_32x32x16_f16 v[48:63], v[2:5], v[92:95], v[48:63]
	ds_read_b128 v[2:5], v141 offset:96
	s_waitcnt lgkmcnt(0)
	v_mfma_f32_32x32x16_f16 v[64:79], v[2:5], v[92:95], v[64:79]
	s_waitcnt vmcnt(0)
	ds_write_b128 v129, v[100:103] offset:18432
	ds_write_b128 v131, v[96:99] offset:18432
	ds_write_b128 v140, v[108:111] offset:27648
	ds_write_b128 v142, v[104:107] offset:27648
	s_nop 8
	v_max3_f32 v0, v48, v49, v50
	v_max3_f32 v2, v51, v52, v53
	v_max3_f32 v3, v54, v55, v56
	v_max3_f32 v4, v57, v58, v59
	v_max3_f32 v0, v0, v60, v61
	v_max3_f32 v2, v2, v62, v63
	v_max3_f32 v3, v3, v64, v65
	v_max3_f32 v4, v4, v66, v67
	v_max3_f32 v0, v0, v68, v69
	v_max3_f32 v2, v2, v70, v71
	v_max3_f32 v3, v3, v72, v73
	v_max3_f32 v4, v4, v74, v75
	v_max3_f32 v0, v0, v76, v77
	v_max3_f32 v2, v2, v78, v79
	v_max3_f32 v0, v0, v2, v3
	v_max_f32_e32 v0, v0, v4
	v_mov_b32_e32 v2, v0
	s_nop 1
	v_permlane32_swap_b32_e32 v0, v2
	v_max_f32_e32 v0, v0, v2
	v_cmp_lt_f32_e32 vcc, s79, v0
	s_cbranch_vccz .LBB0_2739
	v_max_f32_e32 v0, v0, v0
	v_max_f32_e32 v0, 0, v0
	v_exp_f32_e64 v2, -v0
	v_add_f32_e32 v147, v147, v0
	v_xor_b32_e32 v204, 0x80000000, v147
	v_mov_b32_e32 v205, v204
	v_mov_b32_e32 v206, v204
	v_mov_b32_e32 v207, v204
	v_mov_b32_e32 v208, v204
	v_mov_b32_e32 v209, v204
	v_mov_b32_e32 v210, v204
	v_mov_b32_e32 v211, v204
	v_mov_b32_e32 v212, v204
	v_mov_b32_e32 v213, v204
	v_mov_b32_e32 v214, v204
	v_mov_b32_e32 v215, v204
	v_mov_b32_e32 v216, v204
	v_mov_b32_e32 v217, v204
	v_mov_b32_e32 v218, v204
	v_mov_b32_e32 v219, v204
	v_pk_add_f32 v[64:65], v[64:65], v[0:1] op_sel_hi:[1,0] neg_lo:[0,1] neg_hi:[0,1]
	v_pk_add_f32 v[48:49], v[48:49], v[0:1] op_sel_hi:[1,0] neg_lo:[0,1] neg_hi:[0,1]
	v_mul_f32_e32 v153, v153, v2
	v_pk_add_f32 v[66:67], v[66:67], v[0:1] op_sel_hi:[1,0] neg_lo:[0,1] neg_hi:[0,1]
	v_pk_add_f32 v[50:51], v[50:51], v[0:1] op_sel_hi:[1,0] neg_lo:[0,1] neg_hi:[0,1]
	v_pk_add_f32 v[68:69], v[68:69], v[0:1] op_sel_hi:[1,0] neg_lo:[0,1] neg_hi:[0,1]
	v_pk_add_f32 v[52:53], v[52:53], v[0:1] op_sel_hi:[1,0] neg_lo:[0,1] neg_hi:[0,1]
	v_pk_add_f32 v[70:71], v[70:71], v[0:1] op_sel_hi:[1,0] neg_lo:[0,1] neg_hi:[0,1]
	v_pk_add_f32 v[54:55], v[54:55], v[0:1] op_sel_hi:[1,0] neg_lo:[0,1] neg_hi:[0,1]
	v_pk_add_f32 v[72:73], v[72:73], v[0:1] op_sel_hi:[1,0] neg_lo:[0,1] neg_hi:[0,1]
	v_pk_add_f32 v[56:57], v[56:57], v[0:1] op_sel_hi:[1,0] neg_lo:[0,1] neg_hi:[0,1]
	v_pk_add_f32 v[74:75], v[74:75], v[0:1] op_sel_hi:[1,0] neg_lo:[0,1] neg_hi:[0,1]
	v_pk_add_f32 v[58:59], v[58:59], v[0:1] op_sel_hi:[1,0] neg_lo:[0,1] neg_hi:[0,1]
	v_pk_add_f32 v[76:77], v[76:77], v[0:1] op_sel_hi:[1,0] neg_lo:[0,1] neg_hi:[0,1]
	v_pk_add_f32 v[60:61], v[60:61], v[0:1] op_sel_hi:[1,0] neg_lo:[0,1] neg_hi:[0,1]
	v_pk_mul_f32 v[46:47], v[46:47], v[2:3] op_sel_hi:[1,0]
	v_pk_mul_f32 v[44:45], v[44:45], v[2:3] op_sel_hi:[1,0]
	v_pk_mul_f32 v[42:43], v[42:43], v[2:3] op_sel_hi:[1,0]
	v_pk_mul_f32 v[40:41], v[40:41], v[2:3] op_sel_hi:[1,0]
	v_pk_mul_f32 v[38:39], v[38:39], v[2:3] op_sel_hi:[1,0]
	v_pk_mul_f32 v[36:37], v[36:37], v[2:3] op_sel_hi:[1,0]
	v_pk_mul_f32 v[34:35], v[34:35], v[2:3] op_sel_hi:[1,0]
	v_pk_mul_f32 v[32:33], v[32:33], v[2:3] op_sel_hi:[1,0]
	v_pk_mul_f32 v[30:31], v[30:31], v[2:3] op_sel_hi:[1,0]
	v_pk_mul_f32 v[28:29], v[28:29], v[2:3] op_sel_hi:[1,0]
	v_pk_mul_f32 v[26:27], v[26:27], v[2:3] op_sel_hi:[1,0]
	v_pk_mul_f32 v[24:25], v[24:25], v[2:3] op_sel_hi:[1,0]
	v_pk_mul_f32 v[22:23], v[22:23], v[2:3] op_sel_hi:[1,0]
	v_pk_mul_f32 v[20:21], v[20:21], v[2:3] op_sel_hi:[1,0]
	v_pk_mul_f32 v[18:19], v[18:19], v[2:3] op_sel_hi:[1,0]
	v_pk_mul_f32 v[16:17], v[16:17], v[2:3] op_sel_hi:[1,0]
	v_pk_add_f32 v[78:79], v[78:79], v[0:1] op_sel_hi:[1,0] neg_lo:[0,1] neg_hi:[0,1]
	v_pk_add_f32 v[62:63], v[62:63], v[0:1] op_sel_hi:[1,0] neg_lo:[0,1] neg_hi:[0,1]
.LBB0_2739:
	s_cmp_ge_u32 s9, s8
	s_cbranch_scc1 .Lga_a2_done
	s_waitcnt lgkmcnt(0)
	s_ashr_i32 s7, s6, 31
	s_lshl_b64 s[40:41], s[6:7], 1
	global_load_dwordx4 v[100:103], v[220:221], off
	global_load_dwordx4 v[96:99], v[222:223], off
	v_lshl_add_u64 v[2:3], v[134:135], 0, s[40:41]
	v_lshl_add_u64 v[4:5], v[132:133], 0, s[40:41]
	global_load_dwordx4 v[108:111], v[2:3], off
	global_load_dwordx4 v[104:107], v[4:5], off
	v_lshl_add_u64 v[220:221], v[220:221], 0, v[228:229]
	v_lshl_add_u64 v[222:223], v[222:223], 0, v[228:229]
; #define MFMA(a, b, c) __builtin_amdgcn_mfma_f32_32x32x16_f16((a), (b), (c), 0, 0, 0)
; template <int DK, bool MLA>
; DI void attn_item(const h16* __restrict__ Q, const h16* __restrict__ Kp, const h16* __restrict__ Kr, const h16* __restrict__ Vt,
;                   int kbeg, int kend, h16* __restrict__ out, h16* sm) {
;     ...
;     f32x16 st[2];
;     const float negm = -m;
; #pragma unroll
;     for (int i = 0; i < 16; ++i) { st[0][i] = negm; st[1][i] = negm; }
; #pragma unroll
;     for (int ks = 0; ks < DK / 16; ++ks) {
;       h16x8 k0 = *(const h16x8*)(ksm + r * KS + ks * 16 + hh * 8);
;       h16x8 k1 = *(const h16x8*)(ksm + (32 + r) * KS + ks * 16 + hh * 8);
;       st[0] = MFMA(k0, qf[ks], st[0]);
;       st[1] = MFMA(k1, qf[ks], st[1]);
;     }
;     float mx = fmaxf(st[0][0], st[1][0]);
; #pragma unroll
;     for (int i = 1; i < 16; ++i) mx = fmaxf(mx, fmaxf(st[0][i], st[1][i]));
;     mx = x32_max(mx);
;     if (__builtin_amdgcn_ballot_w64(mx > 8.f) != 0) {
;       const float dlt = fmaxf(mx, 0.f);
;       const float alpha = __builtin_amdgcn_exp2f(-dlt);
;       m += dlt;
;       lsum *= alpha;
; #pragma unroll
;       for (int i = 0; i < 16; ++i) { ot[0][i] *= alpha; ot[1][i] *= alpha; st[0][i] -= dlt; st[1][i] -= dlt; }
;     }
;     float ps = 0.f;
; #pragma unroll
;     for (int i = 0; i < 16; ++i) {
;       st[0][i] = __builtin_amdgcn_exp2f(st[0][i]);
;       st[1][i] = __builtin_amdgcn_exp2f(st[1][i]);
;       ps += st[0][i] + st[1][i];
;     }
;     lsum += ps;
; #pragma unroll
;     for (int s4 = 0; s4 < 4; ++s4) {
;       const int kt2 = s4 >> 1, hf = s4 & 1;
;       h16x8 pb;
; #pragma unroll
;       for (int j = 0; j < 8; ++j) pb[j] = (h16)st[kt2][8 * hf + j];
;       const int kb = kt2 * 32 + 16 * hf;
; #pragma unroll
;       for (int dt = 0; dt < 2; ++dt) {
;         const h16* vp = vsm + (dt * 32 + r) * 72 + kb + 4 * hh;
;         h16x4 lo = *(const h16x4*)vp, hi = *(const h16x4*)(vp + 8);
;         h16x8 va = __builtin_shufflevector(lo, hi, 0, 1, 2, 3, 4, 5, 6, 7);
;         ot[dt] = MFMA(va, pb, ot[dt]);
;       }
;     }
.Lga_a2_done:
	v_exp_f32_e32 v166, v64
	v_exp_f32_e32 v13, v65
	v_exp_f32_e32 v15, v66
	v_exp_f32_e32 v152, v67
	v_exp_f32_e32 v156, v68
	v_exp_f32_e32 v157, v69
	v_exp_f32_e32 v168, v70
	v_exp_f32_e32 v160, v71
	v_exp_f32_e32 v12, v60
	v_add_u32_e32 v60, 0x2000, v143
	v_exp_f32_e32 v158, v52
	v_exp_f32_e32 v159, v53
	v_exp_f32_e32 v169, v54
	v_exp_f32_e32 v163, v55
	v_exp_f32_e32 v164, v56
	v_exp_f32_e32 v165, v57
	v_exp_f32_e32 v10, v58
	v_exp_f32_e32 v11, v59
	ds_read_b128 v[52:55], v60 offset:1024
	ds_read_b128 v[56:59], v60 offset:1056
	v_exp_f32_e32 v167, v48
	v_exp_f32_e32 v14, v49
	v_exp_f32_e32 v154, v50
	v_exp_f32_e32 v155, v51
	v_exp_f32_e32 v4, v61
	v_cvt_pk_f16_f32 v51, v168, v160
	v_cvt_pk_f16_f32 v50, v156, v157
	v_cvt_pk_f16_f32 v49, v15, v152
	v_cvt_pk_f16_f32 v48, v166, v13
	v_add_u32_e32 v61, 0x3000, v143
	v_exp_f32_e32 v161, v72
	s_waitcnt lgkmcnt(1)
	v_mfma_f32_32x32x16_f16 v[32:47], v[52:55], v[48:51], v[32:47]
	ds_read_b128 v[52:55], v61 offset:1536
	v_exp_f32_e32 v162, v73
	v_exp_f32_e32 v7, v74
	v_exp_f32_e32 v8, v75
	v_exp_f32_e32 v9, v76
	v_exp_f32_e32 v0, v77
	v_exp_f32_e32 v2, v78
	s_waitcnt lgkmcnt(0)
	v_mfma_f32_32x32x16_f16 v[16:31], v[52:55], v[48:51], v[16:31]
	ds_read_b128 v[52:55], v61 offset:1568
	v_exp_f32_e32 v3, v79
	v_cvt_pk_f16_f32 v50, v9, v0
	v_cvt_pk_f16_f32 v49, v7, v8
	v_cvt_pk_f16_f32 v48, v161, v162
	v_cvt_pk_f16_f32 v51, v2, v3
	v_exp_f32_e32 v5, v62
	v_exp_f32_e32 v6, v63
	s_waitcnt lgkmcnt(0)
	v_mfma_f32_32x32x16_f16 v[16:31], v[52:55], v[48:51], v[16:31]
	ds_read_b128 v[52:55], v60 offset:1088
	s_cmp_ge_u32 s9, s8
	v_mfma_f32_32x32x16_f16 v[32:47], v[56:59], v[48:51], v[32:47]
	v_cvt_pk_f16_f32 v51, v169, v163
	v_cvt_pk_f16_f32 v50, v158, v159
	v_cvt_pk_f16_f32 v49, v154, v155
	v_cvt_pk_f16_f32 v48, v167, v14
	s_waitcnt lgkmcnt(0)
	s_nop 0
	v_mfma_f32_32x32x16_f16 v[32:47], v[52:55], v[48:51], v[32:47]
	ds_read_b128 v[52:55], v61 offset:1600
	s_waitcnt lgkmcnt(0)
	v_mfma_f32_32x32x16_f16 v[16:31], v[52:55], v[48:51], v[16:31]
	ds_read_b128 v[52:55], v60 offset:1120
	v_cvt_pk_f16_f32 v51, v5, v6
	v_cvt_pk_f16_f32 v50, v12, v4
	v_cvt_pk_f16_f32 v49, v10, v11
	v_cvt_pk_f16_f32 v48, v164, v165
	s_waitcnt lgkmcnt(0)
	s_nop 0
	v_mfma_f32_32x32x16_f16 v[32:47], v[52:55], v[48:51], v[32:47]
	ds_read_b128 v[52:55], v61 offset:1632
	s_waitcnt lgkmcnt(0)
	s_barrier
	v_mfma_f32_32x32x16_f16 v[16:31], v[52:55], v[48:51], v[16:31]
.LBB0_2741:
	ds_read_b128 v[170:173], v141 offset:18432
	v_add_f32_e32 v166, v167, v166
	v_add_f32_e32 v166, 0, v166
	v_add_f32_e32 v13, v14, v13
	v_add_f32_e32 v13, v13, v166
	v_add_f32_e32 v14, v154, v15
	v_add_f32_e32 v13, v14, v13
	v_add_f32_e32 v14, v155, v152
	v_add_f32_e32 v13, v14, v13
	v_add_f32_e32 v14, v158, v156
	v_add_f32_e32 v13, v14, v13
	v_add_f32_e32 v14, v159, v157
	v_add_f32_e32 v13, v14, v13
	v_add_f32_e32 v14, v169, v168
	v_add_f32_e32 v13, v14, v13
	v_add_f32_e32 v14, v163, v160
	v_add_f32_e32 v13, v14, v13
	v_add_f32_e32 v14, v164, v161
	ds_read_b128 v[158:161], v141 offset:18528
	s_waitcnt lgkmcnt(1)
	v_mfma_f32_32x32x16_f16 v[64:79], v[170:173], v[80:83], v[204:219]
	ds_read_b128 v[170:173], v141 offset:23040
	v_add_f32_e32 v13, v14, v13
	v_add_f32_e32 v14, v165, v162
	v_add_f32_e32 v13, v14, v13
	v_add_f32_e32 v7, v10, v7
	v_add_f32_e32 v7, v7, v13
	v_add_f32_e32 v8, v11, v8
	v_add_f32_e32 v7, v8, v7
	v_add_f32_e32 v8, v12, v9
	v_add_f32_e32 v7, v8, v7
	ds_read_b128 v[8:11], v141 offset:23136
	s_waitcnt lgkmcnt(1)
	v_mfma_f32_32x32x16_f16 v[48:63], v[170:173], v[80:83], v[204:219]
	ds_read_b128 v[170:173], v141 offset:18464
	ds_read_b128 v[174:177], v141 offset:23072
	ds_read_b128 v[154:157], v141 offset:23104
	v_add_f32_e32 v0, v4, v0
	v_add_f32_e32 v0, v0, v7
	v_add_f32_e32 v2, v5, v2
	v_add_f32_e32 v0, v2, v0
	s_waitcnt lgkmcnt(2)
	v_mfma_f32_32x32x16_f16 v[64:79], v[170:173], v[84:87], v[64:79]
	ds_read_b128 v[170:173], v141 offset:18496
	v_add_f32_e32 v2, v6, v3
	v_add_f32_e32 v0, v2, v0
	v_add_f32_e32 v0, v153, v0
	s_waitcnt lgkmcnt(2)
	v_mfma_f32_32x32x16_f16 v[48:63], v[174:177], v[84:87], v[48:63]
	s_waitcnt lgkmcnt(0)
	v_mfma_f32_32x32x16_f16 v[64:79], v[170:173], v[88:91], v[64:79]
	v_mfma_f32_32x32x16_f16 v[48:63], v[154:157], v[88:91], v[48:63]
	v_mfma_f32_32x32x16_f16 v[64:79], v[158:161], v[92:95], v[64:79]
	v_mfma_f32_32x32x16_f16 v[48:63], v[8:11], v[92:95], v[48:63]
	s_cmp_ge_u32 s38, s8
	s_cbranch_scc1 .Lga_b1_done
	s_waitcnt vmcnt(4)
	ds_write_b128 v129, v[124:127]
	ds_write_b128 v131, v[120:123]
	ds_write_b128 v140, v[116:119] offset:9216
	ds_write_b128 v142, v[112:115] offset:9216
; template <int DK, bool MLA>
; DI void attn_item(const h16* __restrict__ Q, const h16* __restrict__ Kp, const h16* __restrict__ Kr, const h16* __restrict__ Vt,
;                   int kbeg, int kend, h16* __restrict__ out, h16* sm) {
;     ...
;     float mx = fmaxf(st[0][0], st[1][0]);
; #pragma unroll
;     for (int i = 1; i < 16; ++i) mx = fmaxf(mx, fmaxf(st[0][i], st[1][i]));
;     mx = x32_max(mx);
;     if (__builtin_amdgcn_ballot_w64(mx > 8.f) != 0) {
;       const float dlt = fmaxf(mx, 0.f);
;       const float alpha = __builtin_amdgcn_exp2f(-dlt);
;       m += dlt;
;       lsum *= alpha;
; #pragma unroll
;       for (int i = 0; i < 16; ++i) { ot[0][i] *= alpha; ot[1][i] *= alpha; st[0][i] -= dlt; st[1][i] -= dlt; }
;     }
.Lga_b1_done:
	s_nop 10
	v_max3_f32 v2, v64, v65, v66
	v_max3_f32 v3, v67, v68, v69
	v_max3_f32 v4, v70, v71, v72
	v_max3_f32 v5, v73, v74, v75
	v_max3_f32 v2, v2, v76, v77
	v_max3_f32 v3, v3, v78, v79
	v_max3_f32 v4, v4, v48, v49
	v_max3_f32 v5, v5, v50, v51
	v_max3_f32 v2, v2, v52, v53
	v_max3_f32 v3, v3, v54, v55
	v_max3_f32 v4, v4, v56, v57
	v_max3_f32 v5, v5, v58, v59
	v_max3_f32 v2, v2, v60, v61
	v_max3_f32 v3, v3, v62, v63
	v_max3_f32 v2, v2, v3, v4
	v_max_f32_e32 v2, v2, v5
	v_mov_b32_e32 v3, v2
	s_nop 1
	v_permlane32_swap_b32_e32 v2, v3
	v_max_f32_e32 v2, v2, v3
	v_cmp_lt_f32_e32 vcc, s79, v2
	s_cbranch_vccz .LBB0_2734
	v_max_f32_e32 v2, v2, v2
	v_max_f32_e32 v2, 0, v2
	v_exp_f32_e64 v4, -v2
	v_add_f32_e32 v147, v147, v2
	v_xor_b32_e32 v204, 0x80000000, v147
	v_mov_b32_e32 v205, v204
	v_mov_b32_e32 v206, v204
	v_mov_b32_e32 v207, v204
	v_mov_b32_e32 v208, v204
	v_mov_b32_e32 v209, v204
	v_mov_b32_e32 v210, v204
	v_mov_b32_e32 v211, v204
	v_mov_b32_e32 v212, v204
	v_mov_b32_e32 v213, v204
	v_mov_b32_e32 v214, v204
	v_mov_b32_e32 v215, v204
	v_mov_b32_e32 v216, v204
	v_mov_b32_e32 v217, v204
	v_mov_b32_e32 v218, v204
	v_mov_b32_e32 v219, v204
	v_pk_add_f32 v[64:65], v[64:65], v[2:3] op_sel_hi:[1,0] neg_lo:[0,1] neg_hi:[0,1]
	v_pk_add_f32 v[48:49], v[48:49], v[2:3] op_sel_hi:[1,0] neg_lo:[0,1] neg_hi:[0,1]
	v_mul_f32_e32 v0, v0, v4
	v_pk_add_f32 v[66:67], v[66:67], v[2:3] op_sel_hi:[1,0] neg_lo:[0,1] neg_hi:[0,1]
	v_pk_add_f32 v[50:51], v[50:51], v[2:3] op_sel_hi:[1,0] neg_lo:[0,1] neg_hi:[0,1]
	v_pk_add_f32 v[68:69], v[68:69], v[2:3] op_sel_hi:[1,0] neg_lo:[0,1] neg_hi:[0,1]
	v_pk_add_f32 v[52:53], v[52:53], v[2:3] op_sel_hi:[1,0] neg_lo:[0,1] neg_hi:[0,1]
	v_pk_add_f32 v[70:71], v[70:71], v[2:3] op_sel_hi:[1,0] neg_lo:[0,1] neg_hi:[0,1]
	v_pk_add_f32 v[54:55], v[54:55], v[2:3] op_sel_hi:[1,0] neg_lo:[0,1] neg_hi:[0,1]
	v_pk_add_f32 v[72:73], v[72:73], v[2:3] op_sel_hi:[1,0] neg_lo:[0,1] neg_hi:[0,1]
	v_pk_add_f32 v[56:57], v[56:57], v[2:3] op_sel_hi:[1,0] neg_lo:[0,1] neg_hi:[0,1]
	v_pk_add_f32 v[74:75], v[74:75], v[2:3] op_sel_hi:[1,0] neg_lo:[0,1] neg_hi:[0,1]
	v_pk_add_f32 v[58:59], v[58:59], v[2:3] op_sel_hi:[1,0] neg_lo:[0,1] neg_hi:[0,1]
	v_pk_add_f32 v[76:77], v[76:77], v[2:3] op_sel_hi:[1,0] neg_lo:[0,1] neg_hi:[0,1]
	v_pk_add_f32 v[60:61], v[60:61], v[2:3] op_sel_hi:[1,0] neg_lo:[0,1] neg_hi:[0,1]
	v_pk_mul_f32 v[46:47], v[46:47], v[4:5] op_sel_hi:[1,0]
	v_pk_mul_f32 v[44:45], v[44:45], v[4:5] op_sel_hi:[1,0]
	v_pk_mul_f32 v[42:43], v[42:43], v[4:5] op_sel_hi:[1,0]
	v_pk_mul_f32 v[40:41], v[40:41], v[4:5] op_sel_hi:[1,0]
	v_pk_mul_f32 v[38:39], v[38:39], v[4:5] op_sel_hi:[1,0]
	v_pk_mul_f32 v[36:37], v[36:37], v[4:5] op_sel_hi:[1,0]
	v_pk_mul_f32 v[34:35], v[34:35], v[4:5] op_sel_hi:[1,0]
	v_pk_mul_f32 v[32:33], v[32:33], v[4:5] op_sel_hi:[1,0]
	v_pk_mul_f32 v[30:31], v[30:31], v[4:5] op_sel_hi:[1,0]
	v_pk_mul_f32 v[28:29], v[28:29], v[4:5] op_sel_hi:[1,0]
	v_pk_mul_f32 v[26:27], v[26:27], v[4:5] op_sel_hi:[1,0]
	v_pk_mul_f32 v[24:25], v[24:25], v[4:5] op_sel_hi:[1,0]
	v_pk_mul_f32 v[22:23], v[22:23], v[4:5] op_sel_hi:[1,0]
	v_pk_mul_f32 v[20:21], v[20:21], v[4:5] op_sel_hi:[1,0]
	v_pk_mul_f32 v[18:19], v[18:19], v[4:5] op_sel_hi:[1,0]
	v_pk_mul_f32 v[16:17], v[16:17], v[4:5] op_sel_hi:[1,0]
	v_pk_add_f32 v[78:79], v[78:79], v[2:3] op_sel_hi:[1,0] neg_lo:[0,1] neg_hi:[0,1]
	v_pk_add_f32 v[62:63], v[62:63], v[2:3] op_sel_hi:[1,0] neg_lo:[0,1] neg_hi:[0,1]
	s_branch .LBB0_2734

; DI int TIDX() { int t = threadIdx.x; asm volatile("" : "+v"(t)); return t; }
; template <int DK, bool MLA>
; DI void attn_item(const h16* __restrict__ Q, const h16* __restrict__ Kp, const h16* __restrict__ Kr, const h16* __restrict__ Vt,
;                   int kbeg, int kend, h16* __restrict__ out, h16* sm) {
;     ...
;   const int tid = TIDX(), lane = tid & 63, w = tid >> 6, r = lane & 31, hh = lane >> 5;
;   h16x8 qf[DK / 16];
;   {
;     const h16* qr = Q + (size_t)(w * 32 + r) * DK + hh * 8;
; #pragma unroll
;     for (int ks = 0; ks < DK / 16; ++ks) qf[ks] = *(const h16x8*)(qr + ks * 16);
;   }
;   f32x16 ot[2];
; #pragma unroll
;   for (int i = 0; i < 16; ++i) { ot[0][i] = 0.f; ot[1][i] = 0.f; }
;   float m = -1000.f, lsum = 0.f;
;   u32x4 rkA[NCH], rvA[2], rkB[NCH], rvB[2];
;     ...
;   const int ntile = (kend - kbeg) >> 6;
;   ATT_GLOAD(rkA, rvA, kbeg)
;   ATT_GLOAD(rkB, rvB, kbeg + 64)
.LBB0_2744:
	s_and_b64 vcc, exec, s[8:9]
	s_cbranch_vccz .LBB0_2721
	s_add_u32 s6, s27, s10
	s_addc_u32 s7, 0, 0
	s_mulk_i32 s7, 0xc0
	s_mul_hi_u32 s8, s6, 0xc0
	s_add_i32 s8, s8, s7
	s_mulk_i32 s6, 0xc0
	s_add_u32 s6, s15, s6
	v_mov_b32_e32 v17, v203
	s_addc_u32 s7, s16, s8
	s_movk_i32 s2, 0xffe0
	v_ashrrev_i32_e32 v0, 1, v17
	v_bfe_u32 v16, v17, 5, 1
	s_waitcnt vmcnt(4)
	v_bfi_b32 v144, s2, v0, v17
	v_mov_b64_e32 v[2:3], s[6:7]
	v_mad_i64_i32 v[2:3], s[6:7], v144, s29, v[2:3]
	v_lshlrev_b32_e32 v0, 4, v16
	v_lshl_add_u64 v[2:3], v[2:3], 0, v[0:1]
	global_load_dwordx4 v[80:83], v[2:3], off
	global_load_dwordx4 v[84:87], v[2:3], off offset:32
	global_load_dwordx4 v[88:91], v[2:3], off offset:64
	global_load_dwordx4 v[92:95], v[2:3], off offset:96
	global_load_dwordx4 v[96:99], v[2:3], off offset:128
	global_load_dwordx4 v[100:103], v[2:3], off offset:160
	s_mov_b32 s2, 0x2aaaaaab
	v_mul_hi_i32 v0, v17, s2
	v_lshrrev_b32_e32 v2, 31, v0
	v_ashrrev_i32_e32 v0, 1, v0
	v_add_u32_e32 v18, v0, v2
	s_mul_i32 s10, s11, 0x88000
	v_mul_lo_u32 v0, v18, 12
	s_add_u32 s6, s17, s10
	v_sub_u32_e32 v0, v17, v0
	v_add_u32_e32 v148, s26, v18
	s_addc_u32 s7, s18, 0
	v_cmp_gt_i32_e64 s[38:39], 8, v0
	v_cmp_lt_i32_e32 vcc, 7, v0
	v_ashrrev_i32_e32 v149, 31, v148
	v_lshlrev_b32_e32 v2, 3, v0
	s_and_saveexec_b64 s[8:9], vcc
	s_xor_b64 s[8:9], exec, s[8:9]
	v_lshlrev_b64 v[4:5], 6, v[148:149]
	v_lshl_add_u64 v[4:5], s[4:5], 0, v[4:5]
	v_mov_b32_e32 v3, v1
	v_lshl_add_u64 v[4:5], v[2:3], 1, v[4:5]
	v_lshl_add_u64 v[4:5], v[4:5], 0, s[74:75]
	s_or_saveexec_b64 s[8:9], s[8:9]
	v_ashrrev_i32_e32 v3, 31, v2
	s_xor_b64 exec, exec, s[8:9]
	v_lshlrev_b64 v[4:5], 7, v[148:149]
	v_lshl_add_u64 v[4:5], s[6:7], 0, v[4:5]
	v_lshl_add_u64 v[4:5], v[2:3], 1, v[4:5]
	s_or_b64 exec, exec, s[8:9]
	global_load_dwordx4 v[104:107], v[4:5], off
	v_add_u32_e32 v10, 0x100, v17
	v_mul_hi_i32 v0, v10, s2
	v_lshrrev_b32_e32 v4, 31, v0
	v_ashrrev_i32_e32 v0, 1, v0
	v_add_u32_e32 v19, v0, v4
	v_mul_lo_u32 v0, v19, 12
	v_sub_u32_e32 v0, v10, v0
	s_waitcnt vmcnt(10)
	v_add_u32_e32 v150, s26, v19
	v_cmp_gt_i32_e64 s[40:41], 8, v0
	v_cmp_lt_i32_e64 s[44:45], 7, v0
	v_ashrrev_i32_e32 v151, 31, v150
	v_lshlrev_b32_e32 v4, 3, v0
	s_and_saveexec_b64 s[8:9], s[44:45]
	s_xor_b64 s[8:9], exec, s[8:9]
	v_lshlrev_b64 v[6:7], 6, v[150:151]
	v_lshl_add_u64 v[6:7], s[4:5], 0, v[6:7]
	v_mov_b32_e32 v5, v1
	v_lshl_add_u64 v[6:7], v[4:5], 1, v[6:7]
	v_lshl_add_u64 v[6:7], v[6:7], 0, s[74:75]
	s_or_saveexec_b64 s[8:9], s[8:9]
	v_ashrrev_i32_e32 v5, 31, v4
	s_xor_b64 exec, exec, s[8:9]
	v_lshlrev_b64 v[6:7], 7, v[150:151]
	v_lshl_add_u64 v[6:7], s[6:7], 0, v[6:7]
	v_lshl_add_u64 v[6:7], v[4:5], 1, v[6:7]
	s_or_b64 exec, exec, s[8:9]
	global_load_dwordx4 v[108:111], v[6:7], off
	v_add_u32_e32 v0, 0x200, v17
	v_mul_hi_i32 v6, v0, s2
	v_lshrrev_b32_e32 v7, 31, v6
	v_ashrrev_i32_e32 v6, 1, v6
	v_add_u32_e32 v20, v6, v7
	v_mul_lo_u32 v6, v20, 12
	v_sub_u32_e32 v0, v0, v6
	v_add_u32_e32 v152, s26, v20
	v_cmp_gt_i32_e64 s[42:43], 8, v0
	v_cmp_lt_i32_e64 s[46:47], 7, v0
	v_ashrrev_i32_e32 v153, 31, v152
	v_lshlrev_b32_e32 v0, 3, v0
	s_and_saveexec_b64 s[8:9], s[46:47]
	s_xor_b64 s[8:9], exec, s[8:9]
	v_lshlrev_b64 v[6:7], 6, v[152:153]
	v_lshl_add_u64 v[6:7], s[4:5], 0, v[6:7]
	v_lshl_add_u64 v[6:7], v[0:1], 1, v[6:7]
	v_lshl_add_u64 v[6:7], v[6:7], 0, s[74:75]
	s_or_saveexec_b64 s[8:9], s[8:9]
	v_ashrrev_i32_e32 v9, 31, v0
	s_xor_b64 exec, exec, s[8:9]
	v_lshlrev_b64 v[6:7], 7, v[152:153]
	v_lshl_add_u64 v[6:7], s[6:7], 0, v[6:7]
	v_mov_b32_e32 v8, v0
	v_lshl_add_u64 v[6:7], v[8:9], 1, v[6:7]
	s_or_b64 exec, exec, s[8:9]
	s_add_u32 s8, s19, s10
	s_addc_u32 s9, s20, 0
	global_load_dwordx4 v[112:115], v[6:7], off
	s_lshl_b32 s10, s26, 1
	v_lshlrev_b32_e32 v6, 3, v17
	s_add_u32 s8, s8, s10
	v_and_b32_e32 v6, 56, v6
	s_addc_u32 s9, s9, 0
	v_lshlrev_b32_e32 v6, 1, v6
	v_mov_b32_e32 v7, v1
	v_lshl_add_u64 v[12:13], s[8:9], 0, v[6:7]
	v_ashrrev_i32_e32 v21, 3, v17
	s_movk_i32 s2, 0x2200
	v_mad_i64_i32 v[154:155], s[10:11], v21, s2, v[12:13]
	v_ashrrev_i32_e32 v22, 3, v10
	v_mad_i64_i32 v[156:157], s[10:11], v22, s2, v[12:13]
	global_load_dwordx4 v[116:119], v[154:155], off
	global_load_dwordx4 v[120:123], v[156:157], off
	s_or_b32 s27, s26, 64
	v_add_u32_e32 v12, s27, v18
	v_ashrrev_i32_e32 v13, 31, v12
	s_and_saveexec_b64 s[10:11], vcc
	s_xor_b64 s[10:11], exec, s[10:11]
	v_lshlrev_b64 v[10:11], 6, v[12:13]
	v_lshl_add_u64 v[10:11], s[4:5], 0, v[10:11]
	v_mov_b32_e32 v12, v2
	v_mov_b32_e32 v13, v1
	v_lshl_add_u64 v[10:11], v[12:13], 1, v[10:11]
	v_lshl_add_u64 v[10:11], v[10:11], 0, s[74:75]
	s_andn2_saveexec_b64 s[10:11], s[10:11]
	v_lshlrev_b64 v[10:11], 7, v[12:13]
	v_lshl_add_u64 v[10:11], s[6:7], 0, v[10:11]
	v_lshl_add_u64 v[10:11], v[2:3], 1, v[10:11]
	s_or_b64 exec, exec, s[10:11]
	global_load_dwordx4 v[124:127], v[10:11], off
	v_add_u32_e32 v12, s27, v19
	v_ashrrev_i32_e32 v13, 31, v12
	s_and_saveexec_b64 s[10:11], s[44:45]
	s_xor_b64 s[10:11], exec, s[10:11]
	v_lshlrev_b64 v[10:11], 6, v[12:13]
	v_lshl_add_u64 v[10:11], s[4:5], 0, v[10:11]
	v_mov_b32_e32 v12, v4
	v_mov_b32_e32 v13, v1
	v_lshl_add_u64 v[10:11], v[12:13], 1, v[10:11]
	v_lshl_add_u64 v[10:11], v[10:11], 0, s[74:75]
	s_andn2_saveexec_b64 s[10:11], s[10:11]
	v_lshlrev_b64 v[10:11], 7, v[12:13]
	v_lshl_add_u64 v[10:11], s[6:7], 0, v[10:11]
	v_lshl_add_u64 v[10:11], v[4:5], 1, v[10:11]
	s_or_b64 exec, exec, s[10:11]
	global_load_dwordx4 v[128:131], v[10:11], off
	v_add_u32_e32 v14, s27, v20
	v_ashrrev_i32_e32 v15, 31, v14
	s_and_saveexec_b64 s[10:11], s[46:47]
	s_xor_b64 s[10:11], exec, s[10:11]
	v_lshlrev_b64 v[8:9], 6, v[14:15]
	v_lshl_add_u64 v[8:9], s[4:5], 0, v[8:9]
	v_lshl_add_u64 v[8:9], v[0:1], 1, v[8:9]
	v_lshl_add_u64 v[12:13], v[8:9], 0, s[74:75]
	s_or_saveexec_b64 s[10:11], s[10:11]
	v_mov_b64_e32 v[10:11], v[0:1]
	s_xor_b64 exec, exec, s[10:11]
	v_lshlrev_b64 v[10:11], 7, v[14:15]
	v_lshl_add_u64 v[10:11], s[6:7], 0, v[10:11]
	v_mov_b32_e32 v8, v0
	v_lshl_add_u64 v[12:13], v[8:9], 1, v[10:11]
	v_mov_b64_e32 v[10:11], v[8:9]
	s_or_b64 exec, exec, s[10:11]
	v_mad_i64_i32 v[14:15], s[10:11], v22, s2, 0
	v_mad_i64_i32 v[8:9], s[10:11], v21, s2, 0
	global_load_dwordx4 v[132:135], v[12:13], off
	v_lshl_add_u64 v[12:13], s[8:9], 0, v[14:15]
	v_mov_b32_e32 v7, v1
	s_waitcnt vmcnt(16)
; template <int DK, bool MLA>
; DI void attn_item(const h16* __restrict__ Q, const h16* __restrict__ Kp, const h16* __restrict__ Kr, const h16* __restrict__ Vt,
;                   int kbeg, int kend, h16* __restrict__ out, h16* sm) {
;     ...
;   f32x16 ot[2];
; #pragma unroll
;   for (int i = 0; i < 16; ++i) { ot[0][i] = 0.f; ot[1][i] = 0.f; }
;   float m = -1000.f, lsum = 0.f;
;   u32x4 rkA[NCH], rvA[2], rkB[NCH], rvB[2];
;     ...
;   const int ntile = (kend - kbeg) >> 6;
;   ATT_GLOAD(rkA, rvA, kbeg)
;   ATT_GLOAD(rkB, rvB, kbeg + 64)
;   auto tile = [&](int it, u32x4 (&RK)[NCH], u32x4 (&RV)[2]) {
;     h16* ksm = sm + (it & 1) * BUF;
;     h16* vsm = ksm + 64 * KS;
; #pragma unroll
;     for (int i = 0; i < NCH; ++i) {
;       const int c = tid + 256 * i, key = c / NKC, part = c % NKC;
;       *(u32x4*)(ksm + key * KS + part * 8) = RK[i];
;     }
; #pragma unroll
;     for (int i = 0; i < 2; ++i) {
;       const int c = tid + 256 * i, dv = c >> 3, kc = c & 7;
;       *(u32x4*)(vsm + dv * 72 + kc * 8) = RV[i];
;     }
;     __syncthreads();
;     if (it + 2 < ntile) ATT_GLOAD(RK, RV, kbeg + (it + 2) * 64)
	v_lshl_add_u64 v[158:159], v[12:13], 0, v[6:7]
	v_lshl_add_u64 v[8:9], s[8:9], 0, v[8:9]
	v_lshl_add_u64 v[160:161], v[8:9], 0, v[6:7]
	global_load_dwordx4 v[136:139], v[158:159], off offset:128
	global_load_dwordx4 v[140:143], v[160:161], off offset:128
	s_movk_i32 s2, 0xd0
	v_mul_lo_u32 v7, v18, s2
	s_waitcnt vmcnt(16)
	v_lshl_add_u32 v147, v2, 1, v7
	v_mul_lo_u32 v7, v19, s2
	v_and_b32_e32 v8, 31, v17
	v_lshl_add_u32 v149, v4, 1, v7
	v_mul_lo_u32 v7, v20, s2
	v_lshl_add_u32 v151, v0, 1, v7
	v_lshl_add_u64 v[174:175], v[0:1], 1, s[4:5]
	v_mul_u32_u24_e32 v0, 0x68, v8
	v_lshlrev_b32_e32 v9, 3, v16
	v_mad_u64_u32 v[162:163], s[10:11], v21, s28, v[6:7]
	v_lshlrev_b32_e32 v0, 1, v0
	v_mad_u64_u32 v[164:165], s[10:11], v22, s28, v[6:7]
	v_mov_b32_e32 v6, v2
	v_mov_b32_e32 v7, v1
	v_lshl_add_u64 v[168:169], v[2:3], 1, s[6:7]
	v_mov_b32_e32 v2, v4
	v_mov_b32_e32 v3, v1
	v_lshl_add_u32 v163, v9, 1, v0
	v_mul_u32_u24_e32 v0, 0x48, v8
	v_mov_b32_e32 v14, v1
	v_mov_b32_e32 v15, v1
	s_sub_i32 s8, 0x1100, s26
	v_lshl_add_u64 v[166:167], v[6:7], 1, s[4:5]
	v_lshl_add_u64 v[170:171], v[2:3], 1, s[4:5]
	v_lshl_add_u64 v[172:173], v[4:5], 1, s[6:7]
	v_lshl_add_u64 v[176:177], v[10:11], 1, s[6:7]
	v_lshlrev_b32_e32 v146, 2, v16
	v_lshlrev_b32_e32 v165, 1, v9
	v_lshl_add_u32 v165, v0, 1, v165
	v_mov_b32_e32 v0, v1
	v_mov_b32_e32 v2, v1
	v_mov_b32_e32 v4, v1
	v_mov_b32_e32 v5, v1
	v_mov_b32_e32 v6, v1
	v_mov_b32_e32 v8, v1
	v_mov_b32_e32 v9, v1
	v_mov_b32_e32 v10, v1
	v_mov_b32_e32 v11, v1
	v_mov_b32_e32 v12, v1
	v_mov_b32_e32 v13, v1
	v_mov_b64_e32 v[30:31], v[14:15]
	v_mov_b64_e32 v[46:47], v[14:15]
	v_ashrrev_i32_e32 v145, 31, v144
	s_lshr_b32 s8, s8, 6
	s_mov_b32 s9, 3
	v_mov_b32_e32 v178, 0xc47a0000
	v_mov_b32_e32 v153, 0
	s_movk_i32 s6, 0xc0
	v_mov_b64_e32 v[28:29], v[12:13]
	v_mov_b64_e32 v[26:27], v[10:11]
	v_mov_b64_e32 v[24:25], v[8:9]
	v_mov_b64_e32 v[22:23], v[6:7]
	v_mov_b64_e32 v[20:21], v[4:5]
	v_mov_b64_e32 v[18:19], v[2:3]
	v_mov_b64_e32 v[16:17], v[0:1]
	v_mov_b64_e32 v[44:45], v[12:13]
	v_mov_b64_e32 v[42:43], v[10:11]
	v_mov_b64_e32 v[40:41], v[8:9]
	v_mov_b64_e32 v[38:39], v[6:7]
	v_mov_b64_e32 v[36:37], v[4:5]
	v_mov_b64_e32 v[34:35], v[2:3]
	v_mov_b64_e32 v[32:33], v[0:1]
	v_mov_b32_e32 v204, 0x447a0000
	v_mov_b32_e32 v205, 0x447a0000
	v_mov_b32_e32 v206, 0x447a0000
	v_mov_b32_e32 v207, 0x447a0000
	v_mov_b32_e32 v208, 0x447a0000
	v_mov_b32_e32 v209, 0x447a0000
	v_mov_b32_e32 v210, 0x447a0000
	v_mov_b32_e32 v211, 0x447a0000
	v_mov_b32_e32 v212, 0x447a0000
	v_mov_b32_e32 v213, 0x447a0000
	v_mov_b32_e32 v214, 0x447a0000
	v_mov_b32_e32 v215, 0x447a0000
	v_mov_b32_e32 v216, 0x447a0000
	v_mov_b32_e32 v217, 0x447a0000
	v_mov_b32_e32 v218, 0x447a0000
	v_mov_b32_e32 v219, 0x447a0000
	s_movk_i32 s26, 0x80
	v_add_u32_e32 v2, s26, v148
	v_ashrrev_i32_e32 v3, 31, v2
	v_lshlrev_b64 v[4:5], 7, v[2:3]
	v_lshlrev_b64 v[2:3], 6, v[2:3]
	v_lshl_add_u64 v[2:3], v[166:167], 0, v[2:3]
	v_lshl_add_u64 v[4:5], v[168:169], 0, v[4:5]
	v_lshl_add_u64 v[2:3], v[2:3], 0, s[74:75]
	v_cndmask_b32_e64 v221, v3, v5, s[38:39]
	v_cndmask_b32_e64 v220, v2, v4, s[38:39]
	v_mov_b32_e32 v2, 0x1000
	v_mov_b32_e32 v3, 0x2000
	v_cndmask_b32_e64 v228, v2, v3, s[38:39]
	v_mov_b32_e32 v229, 0
	v_add_u32_e32 v2, s26, v150
	v_ashrrev_i32_e32 v3, 31, v2
	v_lshlrev_b64 v[4:5], 7, v[2:3]
	v_lshlrev_b64 v[2:3], 6, v[2:3]
	v_lshl_add_u64 v[2:3], v[170:171], 0, v[2:3]
	v_lshl_add_u64 v[4:5], v[172:173], 0, v[4:5]
	v_lshl_add_u64 v[2:3], v[2:3], 0, s[74:75]
	v_cndmask_b32_e64 v223, v3, v5, s[40:41]
	v_cndmask_b32_e64 v222, v2, v4, s[40:41]
	v_mov_b32_e32 v2, 0x1000
	v_mov_b32_e32 v3, 0x2000
	v_cndmask_b32_e64 v230, v2, v3, s[40:41]
	v_mov_b32_e32 v231, 0
	v_add_u32_e32 v2, s26, v152
	v_ashrrev_i32_e32 v3, 31, v2
	v_lshlrev_b64 v[4:5], 7, v[2:3]
	v_lshlrev_b64 v[2:3], 6, v[2:3]
	v_lshl_add_u64 v[2:3], v[174:175], 0, v[2:3]
	v_lshl_add_u64 v[4:5], v[176:177], 0, v[4:5]
	v_lshl_add_u64 v[2:3], v[2:3], 0, s[74:75]
	v_cndmask_b32_e64 v227, v3, v5, s[42:43]
	v_cndmask_b32_e64 v226, v2, v4, s[42:43]
	v_mov_b32_e32 v2, 0x1000
	v_mov_b32_e32 v3, 0x2000
	v_cndmask_b32_e64 v232, v2, v3, s[42:43]
	v_mov_b32_e32 v233, 0
	s_waitcnt vmcnt(0)
	ds_write_b128 v147, v[104:107]
	ds_write_b128 v149, v[108:111]
	ds_write_b128 v151, v[112:115]
	ds_write_b128 v162, v[116:119] offset:13312
	ds_write_b128 v164, v[120:123] offset:13312
	s_add_i32 s10, s9, -1
	s_cmp_ge_u32 s10, s8
	s_cbranch_scc1 .Lma_e_done
	s_waitcnt lgkmcnt(0)
	s_sub_i32 s26, s6, 64
	s_ashr_i32 s27, s26, 31
	s_lshl_b64 s[26:27], s[26:27], 1
	global_load_dwordx4 v[104:107], v[220:221], off
	global_load_dwordx4 v[108:111], v[222:223], off
	global_load_dwordx4 v[112:115], v[226:227], off
	v_lshl_add_u64 v[2:3], v[160:161], 0, s[26:27]
	v_lshl_add_u64 v[4:5], v[158:159], 0, s[26:27]
	global_load_dwordx4 v[116:119], v[2:3], off
	global_load_dwordx4 v[120:123], v[4:5], off
	v_lshl_add_u64 v[220:221], v[220:221], 0, v[228:229]
	v_lshl_add_u64 v[222:223], v[222:223], 0, v[230:231]
	v_lshl_add_u64 v[226:227], v[226:227], 0, v[232:233]

; template <int DK, bool MLA>
; DI void attn_item(const h16* __restrict__ Q, const h16* __restrict__ Kp, const h16* __restrict__ Kr, const h16* __restrict__ Vt,
;                   int kbeg, int kend, h16* __restrict__ out, h16* sm) {
;     ...
;   const int ntile = (kend - kbeg) >> 6;
;   ATT_GLOAD(rkA, rvA, kbeg)
;   ATT_GLOAD(rkB, rvB, kbeg + 64)
;   auto tile = [&](int it, u32x4 (&RK)[NCH], u32x4 (&RV)[2]) {
;     h16* ksm = sm + (it & 1) * BUF;
;     h16* vsm = ksm + 64 * KS;
; #pragma unroll
;     for (int i = 0; i < NCH; ++i) {
;       const int c = tid + 256 * i, key = c / NKC, part = c % NKC;
;       *(u32x4*)(ksm + key * KS + part * 8) = RK[i];
;     }
; #pragma unroll
;     for (int i = 0; i < 2; ++i) {
;       const int c = tid + 256 * i, dv = c >> 3, kc = c & 7;
;       *(u32x4*)(vsm + dv * 72 + kc * 8) = RV[i];
;     }
;     __syncthreads();
;     if (it + 2 < ntile) ATT_GLOAD(RK, RV, kbeg + (it + 2) * 64)
.LBB0_2770:
	s_add_i32 s26, s9, 1
	s_cmp_ge_u32 s26, s8
	s_cbranch_scc1 .Lma_b2_done
	s_waitcnt lgkmcnt(0)
	s_add_i32 s26, s6, 64
	s_ashr_i32 s27, s26, 31
	s_lshl_b64 s[26:27], s[26:27], 1
	global_load_dwordx4 v[104:107], v[220:221], off
	global_load_dwordx4 v[108:111], v[222:223], off
	global_load_dwordx4 v[112:115], v[226:227], off
	v_lshl_add_u64 v[2:3], v[160:161], 0, s[26:27]
	v_lshl_add_u64 v[4:5], v[158:159], 0, s[26:27]
	global_load_dwordx4 v[116:119], v[2:3], off
	global_load_dwordx4 v[120:123], v[4:5], off
	v_lshl_add_u64 v[220:221], v[220:221], 0, v[228:229]
	v_lshl_add_u64 v[222:223], v[222:223], 0, v[230:231]
	v_lshl_add_u64 v[226:227], v[226:227], 0, v[232:233]

; #define MFMA(a, b, c) __builtin_amdgcn_mfma_f32_32x32x16_f16((a), (b), (c), 0, 0, 0)
; template <int DK, bool MLA>
; DI void attn_item(const h16* __restrict__ Q, const h16* __restrict__ Kp, const h16* __restrict__ Kr, const h16* __restrict__ Vt,
;                   int kbeg, int kend, h16* __restrict__ out, h16* sm) {
;     ...
; #pragma unroll
;     for (int i = 0; i < NCH; ++i) {
;       const int c = tid + 256 * i, key = c / NKC, part = c % NKC;
;       *(u32x4*)(ksm + key * KS + part * 8) = RK[i];
;     }
; #pragma unroll
;     for (int i = 0; i < 2; ++i) {
;       const int c = tid + 256 * i, dv = c >> 3, kc = c & 7;
;       *(u32x4*)(vsm + dv * 72 + kc * 8) = RV[i];
;     }
;     __syncthreads();
;     if (it + 2 < ntile) ATT_GLOAD(RK, RV, kbeg + (it + 2) * 64)
;     f32x16 st[2];
;     const float negm = -m;
; #pragma unroll
;     for (int i = 0; i < 16; ++i) { st[0][i] = negm; st[1][i] = negm; }
; #pragma unroll
;     for (int ks = 0; ks < DK / 16; ++ks) {
;       h16x8 k0 = *(const h16x8*)(ksm + r * KS + ks * 16 + hh * 8);
;       h16x8 k1 = *(const h16x8*)(ksm + (32 + r) * KS + ks * 16 + hh * 8);
;       st[0] = MFMA(k0, qf[ks], st[0]);
;       st[1] = MFMA(k1, qf[ks], st[1]);
;     }
;     float mx = fmaxf(st[0][0], st[1][0]);
; #pragma unroll
;     for (int i = 1; i < 16; ++i) mx = fmaxf(mx, fmaxf(st[0][i], st[1][i]));
;     mx = x32_max(mx);
;     if (__builtin_amdgcn_ballot_w64(mx > 8.f) != 0) {
;       const float dlt = fmaxf(mx, 0.f);
;       const float alpha = __builtin_amdgcn_exp2f(-dlt);
;       m += dlt;
;       lsum *= alpha;
; #pragma unroll
;       for (int i = 0; i < 16; ++i) { ot[0][i] *= alpha; ot[1][i] *= alpha; st[0][i] -= dlt; st[1][i] -= dlt; }
;     }
.LBB0_2771:
	s_add_i32 s10, s9, -1
	s_cmp_ge_u32 s10, s8
	s_waitcnt lgkmcnt(0)
	s_barrier
.LBB0_2773:
	ds_read_b128 v[2:5], v163
	s_waitcnt lgkmcnt(0)
	s_nop 0
	v_mfma_f32_32x32x16_f16 v[64:79], v[2:5], v[80:83], v[204:219]
	ds_read_b128 v[2:5], v163 offset:6656
	s_waitcnt lgkmcnt(0)
	v_mfma_f32_32x32x16_f16 v[48:63], v[2:5], v[80:83], v[204:219]
	ds_read_b128 v[2:5], v163 offset:32
	s_waitcnt lgkmcnt(0)
	v_mfma_f32_32x32x16_f16 v[64:79], v[2:5], v[84:87], v[64:79]
	ds_read_b128 v[2:5], v163 offset:6688
	s_waitcnt lgkmcnt(0)
	v_mfma_f32_32x32x16_f16 v[48:63], v[2:5], v[84:87], v[48:63]
	ds_read_b128 v[2:5], v163 offset:64
	s_waitcnt lgkmcnt(0)
	v_mfma_f32_32x32x16_f16 v[64:79], v[2:5], v[88:91], v[64:79]
	ds_read_b128 v[2:5], v163 offset:6720
	s_waitcnt lgkmcnt(0)
	v_mfma_f32_32x32x16_f16 v[48:63], v[2:5], v[88:91], v[48:63]
	ds_read_b128 v[2:5], v163 offset:96
	s_waitcnt lgkmcnt(0)
	v_mfma_f32_32x32x16_f16 v[64:79], v[2:5], v[92:95], v[64:79]
	ds_read_b128 v[2:5], v163 offset:6752
	s_waitcnt lgkmcnt(0)
	v_mfma_f32_32x32x16_f16 v[48:63], v[2:5], v[92:95], v[48:63]
	ds_read_b128 v[2:5], v163 offset:128
	s_waitcnt lgkmcnt(0)
	v_mfma_f32_32x32x16_f16 v[64:79], v[2:5], v[96:99], v[64:79]
	ds_read_b128 v[2:5], v163 offset:6784
	s_waitcnt lgkmcnt(0)
	v_mfma_f32_32x32x16_f16 v[48:63], v[2:5], v[96:99], v[48:63]
	ds_read_b128 v[2:5], v163 offset:6816
	s_waitcnt lgkmcnt(0)
	v_mfma_f32_32x32x16_f16 v[48:63], v[2:5], v[100:103], v[48:63]
	ds_read_b128 v[2:5], v163 offset:160
	s_waitcnt lgkmcnt(0)
	v_mfma_f32_32x32x16_f16 v[64:79], v[2:5], v[100:103], v[64:79]
	s_waitcnt vmcnt(0)
	ds_write_b128 v147, v[124:127] offset:22528
	ds_write_b128 v149, v[128:131] offset:22528
	ds_write_b128 v151, v[132:135] offset:22528
	ds_write_b128 v162, v[140:143] offset:35840
	ds_write_b128 v164, v[136:139] offset:35840
	s_nop 8
	v_max3_f32 v0, v48, v49, v50
	v_max3_f32 v2, v51, v52, v53
	v_max3_f32 v3, v54, v55, v56
	v_max3_f32 v4, v57, v58, v59
	v_max3_f32 v0, v0, v60, v61
	v_max3_f32 v2, v2, v62, v63
	v_max3_f32 v3, v3, v64, v65
	v_max3_f32 v4, v4, v66, v67
	v_max3_f32 v0, v0, v68, v69
	v_max3_f32 v2, v2, v70, v71
	v_max3_f32 v3, v3, v72, v73
	v_max3_f32 v4, v4, v74, v75
	v_max3_f32 v0, v0, v76, v77
	v_max3_f32 v2, v2, v78, v79
	v_max3_f32 v0, v0, v2, v3
	v_max_f32_e32 v0, v0, v4
	v_mov_b32_e32 v2, v0
	s_nop 1
	v_permlane32_swap_b32_e32 v0, v2
	v_max_f32_e32 v0, v0, v2
	v_cmp_lt_f32_e32 vcc, s79, v0
	s_cbranch_vccz .LBB0_2775
	v_max_f32_e32 v0, v0, v0
	v_max_f32_e32 v0, 0, v0
	v_exp_f32_e64 v2, -v0
	v_add_f32_e32 v178, v178, v0
	v_xor_b32_e32 v204, 0x80000000, v178
	v_mov_b32_e32 v205, v204
	v_mov_b32_e32 v206, v204
	v_mov_b32_e32 v207, v204
	v_mov_b32_e32 v208, v204
	v_mov_b32_e32 v209, v204
	v_mov_b32_e32 v210, v204
	v_mov_b32_e32 v211, v204
	v_mov_b32_e32 v212, v204
	v_mov_b32_e32 v213, v204
	v_mov_b32_e32 v214, v204
	v_mov_b32_e32 v215, v204
	v_mov_b32_e32 v216, v204
	v_mov_b32_e32 v217, v204
	v_mov_b32_e32 v218, v204
	v_mov_b32_e32 v219, v204
	v_pk_add_f32 v[64:65], v[64:65], v[0:1] op_sel_hi:[1,0] neg_lo:[0,1] neg_hi:[0,1]
	v_pk_add_f32 v[48:49], v[48:49], v[0:1] op_sel_hi:[1,0] neg_lo:[0,1] neg_hi:[0,1]
	v_mul_f32_e32 v153, v153, v2
	v_pk_add_f32 v[66:67], v[66:67], v[0:1] op_sel_hi:[1,0] neg_lo:[0,1] neg_hi:[0,1]
	v_pk_add_f32 v[50:51], v[50:51], v[0:1] op_sel_hi:[1,0] neg_lo:[0,1] neg_hi:[0,1]
	v_pk_add_f32 v[68:69], v[68:69], v[0:1] op_sel_hi:[1,0] neg_lo:[0,1] neg_hi:[0,1]
	v_pk_add_f32 v[52:53], v[52:53], v[0:1] op_sel_hi:[1,0] neg_lo:[0,1] neg_hi:[0,1]
	v_pk_add_f32 v[70:71], v[70:71], v[0:1] op_sel_hi:[1,0] neg_lo:[0,1] neg_hi:[0,1]
	v_pk_add_f32 v[54:55], v[54:55], v[0:1] op_sel_hi:[1,0] neg_lo:[0,1] neg_hi:[0,1]
	v_pk_add_f32 v[72:73], v[72:73], v[0:1] op_sel_hi:[1,0] neg_lo:[0,1] neg_hi:[0,1]
	v_pk_add_f32 v[56:57], v[56:57], v[0:1] op_sel_hi:[1,0] neg_lo:[0,1] neg_hi:[0,1]
	v_pk_add_f32 v[74:75], v[74:75], v[0:1] op_sel_hi:[1,0] neg_lo:[0,1] neg_hi:[0,1]
	v_pk_add_f32 v[58:59], v[58:59], v[0:1] op_sel_hi:[1,0] neg_lo:[0,1] neg_hi:[0,1]
	v_pk_add_f32 v[76:77], v[76:77], v[0:1] op_sel_hi:[1,0] neg_lo:[0,1] neg_hi:[0,1]
	v_pk_add_f32 v[60:61], v[60:61], v[0:1] op_sel_hi:[1,0] neg_lo:[0,1] neg_hi:[0,1]
	v_pk_mul_f32 v[46:47], v[46:47], v[2:3] op_sel_hi:[1,0]
	v_pk_mul_f32 v[44:45], v[44:45], v[2:3] op_sel_hi:[1,0]
	v_pk_mul_f32 v[42:43], v[42:43], v[2:3] op_sel_hi:[1,0]
	v_pk_mul_f32 v[40:41], v[40:41], v[2:3] op_sel_hi:[1,0]
	v_pk_mul_f32 v[38:39], v[38:39], v[2:3] op_sel_hi:[1,0]
	v_pk_mul_f32 v[36:37], v[36:37], v[2:3] op_sel_hi:[1,0]
	v_pk_mul_f32 v[34:35], v[34:35], v[2:3] op_sel_hi:[1,0]
	v_pk_mul_f32 v[32:33], v[32:33], v[2:3] op_sel_hi:[1,0]
	v_pk_mul_f32 v[30:31], v[30:31], v[2:3] op_sel_hi:[1,0]
	v_pk_mul_f32 v[28:29], v[28:29], v[2:3] op_sel_hi:[1,0]
	v_pk_mul_f32 v[26:27], v[26:27], v[2:3] op_sel_hi:[1,0]
	v_pk_mul_f32 v[24:25], v[24:25], v[2:3] op_sel_hi:[1,0]
	v_pk_mul_f32 v[22:23], v[22:23], v[2:3] op_sel_hi:[1,0]
	v_pk_mul_f32 v[20:21], v[20:21], v[2:3] op_sel_hi:[1,0]
	v_pk_mul_f32 v[18:19], v[18:19], v[2:3] op_sel_hi:[1,0]
	v_pk_mul_f32 v[16:17], v[16:17], v[2:3] op_sel_hi:[1,0]
	v_pk_add_f32 v[78:79], v[78:79], v[0:1] op_sel_hi:[1,0] neg_lo:[0,1] neg_hi:[0,1]
	v_pk_add_f32 v[62:63], v[62:63], v[0:1] op_sel_hi:[1,0] neg_lo:[0,1] neg_hi:[0,1]
.LBB0_2775:
	s_cmp_ge_u32 s9, s8
	s_cbranch_scc1 .Lma_a2_done
	s_waitcnt lgkmcnt(0)
	s_ashr_i32 s7, s6, 31
	s_lshl_b64 s[26:27], s[6:7], 1
	global_load_dwordx4 v[124:127], v[220:221], off
	global_load_dwordx4 v[128:131], v[222:223], off
	global_load_dwordx4 v[132:135], v[226:227], off
	v_lshl_add_u64 v[2:3], v[154:155], 0, s[26:27]
	v_lshl_add_u64 v[4:5], v[156:157], 0, s[26:27]
	global_load_dwordx4 v[140:143], v[2:3], off
	global_load_dwordx4 v[136:139], v[4:5], off
	v_lshl_add_u64 v[220:221], v[220:221], 0, v[228:229]
	v_lshl_add_u64 v[222:223], v[222:223], 0, v[230:231]
	v_lshl_add_u64 v[226:227], v[226:227], 0, v[232:233]
; #define MFMA(a, b, c) __builtin_amdgcn_mfma_f32_32x32x16_f16((a), (b), (c), 0, 0, 0)
; template <int DK, bool MLA>
; DI void attn_item(const h16* __restrict__ Q, const h16* __restrict__ Kp, const h16* __restrict__ Kr, const h16* __restrict__ Vt,
;                   int kbeg, int kend, h16* __restrict__ out, h16* sm) {
;     ...
;     f32x16 st[2];
;     const float negm = -m;
; #pragma unroll
;     for (int i = 0; i < 16; ++i) { st[0][i] = negm; st[1][i] = negm; }
; #pragma unroll
;     for (int ks = 0; ks < DK / 16; ++ks) {
;       h16x8 k0 = *(const h16x8*)(ksm + r * KS + ks * 16 + hh * 8);
;       h16x8 k1 = *(const h16x8*)(ksm + (32 + r) * KS + ks * 16 + hh * 8);
;       st[0] = MFMA(k0, qf[ks], st[0]);
;       st[1] = MFMA(k1, qf[ks], st[1]);
;     }
;     float mx = fmaxf(st[0][0], st[1][0]);
; #pragma unroll
;     for (int i = 1; i < 16; ++i) mx = fmaxf(mx, fmaxf(st[0][i], st[1][i]));
;     mx = x32_max(mx);
;     if (__builtin_amdgcn_ballot_w64(mx > 8.f) != 0) {
;       const float dlt = fmaxf(mx, 0.f);
;       const float alpha = __builtin_amdgcn_exp2f(-dlt);
;       m += dlt;
;       lsum *= alpha;
; #pragma unroll
;       for (int i = 0; i < 16; ++i) { ot[0][i] *= alpha; ot[1][i] *= alpha; st[0][i] -= dlt; st[1][i] -= dlt; }
;     }
;     float ps = 0.f;
; #pragma unroll
;     for (int i = 0; i < 16; ++i) {
;       st[0][i] = __builtin_amdgcn_exp2f(st[0][i]);
;       st[1][i] = __builtin_amdgcn_exp2f(st[1][i]);
;       ps += st[0][i] + st[1][i];
;     }
;     lsum += ps;
; #pragma unroll
;     for (int s4 = 0; s4 < 4; ++s4) {
;       const int kt2 = s4 >> 1, hf = s4 & 1;
;       h16x8 pb;
; #pragma unroll
;       for (int j = 0; j < 8; ++j) pb[j] = (h16)st[kt2][8 * hf + j];
;       const int kb = kt2 * 32 + 16 * hf;
; #pragma unroll
;       for (int dt = 0; dt < 2; ++dt) {
;         const h16* vp = vsm + (dt * 32 + r) * 72 + kb + 4 * hh;
;         h16x4 lo = *(const h16x4*)vp, hi = *(const h16x4*)(vp + 8);
;         h16x8 va = __builtin_shufflevector(lo, hi, 0, 1, 2, 3, 4, 5, 6, 7);
;         ot[dt] = MFMA(va, pb, ot[dt]);
;       }
;     }
.Lma_a2_done:
	v_exp_f32_e32 v192, v64
	v_exp_f32_e32 v193, v65
	v_exp_f32_e32 v5, v66
	v_exp_f32_e32 v6, v67
	v_exp_f32_e32 v186, v68
	v_exp_f32_e32 v9, v69
	v_exp_f32_e32 v188, v70
	v_exp_f32_e32 v189, v71
	v_exp_f32_e32 v15, v60
	v_add_u32_e32 v60, 0x3000, v165
	v_exp_f32_e32 v187, v52
	v_exp_f32_e32 v13, v53
	v_exp_f32_e32 v190, v54
	v_exp_f32_e32 v191, v55
	v_exp_f32_e32 v183, v56
	v_exp_f32_e32 v184, v57
	v_exp_f32_e32 v185, v58
	v_exp_f32_e32 v14, v59
	ds_read_b128 v[52:55], v60 offset:1024
	ds_read_b128 v[56:59], v60 offset:1056
	v_exp_f32_e32 v194, v48
	v_exp_f32_e32 v195, v49
	v_exp_f32_e32 v7, v50
	v_exp_f32_e32 v8, v51
	v_exp_f32_e32 v179, v61
	v_cvt_pk_f16_f32 v51, v188, v189
	v_cvt_pk_f16_f32 v50, v186, v9
	v_cvt_pk_f16_f32 v49, v5, v6
	v_cvt_pk_f16_f32 v48, v192, v193
	v_add_u32_e32 v61, 0x4000, v165
	v_exp_f32_e32 v180, v72
	s_waitcnt lgkmcnt(1)
	v_mfma_f32_32x32x16_f16 v[32:47], v[52:55], v[48:51], v[32:47]
	ds_read_b128 v[52:55], v61 offset:1536
	v_exp_f32_e32 v181, v73
	v_exp_f32_e32 v182, v74
	v_exp_f32_e32 v10, v75
	v_exp_f32_e32 v11, v76
	v_exp_f32_e32 v12, v77
	v_exp_f32_e32 v0, v78
	s_waitcnt lgkmcnt(0)
	v_mfma_f32_32x32x16_f16 v[16:31], v[52:55], v[48:51], v[16:31]
	ds_read_b128 v[52:55], v61 offset:1568
	v_exp_f32_e32 v2, v79
	v_cvt_pk_f16_f32 v50, v11, v12
	v_cvt_pk_f16_f32 v49, v182, v10
	v_cvt_pk_f16_f32 v48, v180, v181
	v_cvt_pk_f16_f32 v51, v0, v2
	v_exp_f32_e32 v3, v62
	v_exp_f32_e32 v4, v63
	s_waitcnt lgkmcnt(0)
	v_mfma_f32_32x32x16_f16 v[16:31], v[52:55], v[48:51], v[16:31]
	ds_read_b128 v[52:55], v60 offset:1088
	s_cmp_ge_u32 s9, s8
	v_mfma_f32_32x32x16_f16 v[32:47], v[56:59], v[48:51], v[32:47]
	v_cvt_pk_f16_f32 v51, v190, v191
	v_cvt_pk_f16_f32 v50, v187, v13
	v_cvt_pk_f16_f32 v49, v7, v8
	v_cvt_pk_f16_f32 v48, v194, v195
	s_waitcnt lgkmcnt(0)
	s_nop 0
	v_mfma_f32_32x32x16_f16 v[32:47], v[52:55], v[48:51], v[32:47]
	ds_read_b128 v[52:55], v61 offset:1600
	s_waitcnt lgkmcnt(0)
	v_mfma_f32_32x32x16_f16 v[16:31], v[52:55], v[48:51], v[16:31]
	ds_read_b128 v[52:55], v60 offset:1120
	v_cvt_pk_f16_f32 v51, v3, v4
	v_cvt_pk_f16_f32 v50, v15, v179
	v_cvt_pk_f16_f32 v49, v185, v14
	v_cvt_pk_f16_f32 v48, v183, v184
	s_waitcnt lgkmcnt(0)
	s_nop 0
	v_mfma_f32_32x32x16_f16 v[32:47], v[52:55], v[48:51], v[32:47]
	ds_read_b128 v[52:55], v61 offset:1632
	s_waitcnt lgkmcnt(0)
	s_barrier
	v_mfma_f32_32x32x16_f16 v[16:31], v[52:55], v[48:51], v[16:31]
.LBB0_2777:
	ds_read_b128 v[196:199], v163 offset:22528
	v_add_f32_e32 v192, v194, v192
	v_add_f32_e32 v200, 0, v192
	v_add_f32_e32 v201, v195, v193
	ds_read_b128 v[192:195], v163 offset:29280
	s_waitcnt lgkmcnt(1)
	v_mfma_f32_32x32x16_f16 v[64:79], v[196:199], v[80:83], v[204:219]
	ds_read_b128 v[196:199], v163 offset:29184
	v_add_f32_e32 v5, v7, v5
	v_add_f32_e32 v6, v8, v6
	v_add_f32_e32 v0, v3, v0
	v_add_f32_e32 v2, v4, v2
	s_waitcnt lgkmcnt(0)
	v_mfma_f32_32x32x16_f16 v[48:63], v[196:199], v[80:83], v[204:219]
	ds_read_b128 v[196:199], v163 offset:22560
	s_waitcnt lgkmcnt(0)
	v_mfma_f32_32x32x16_f16 v[64:79], v[196:199], v[84:87], v[64:79]
	ds_read_b128 v[196:199], v163 offset:29216
	s_waitcnt lgkmcnt(0)
	v_mfma_f32_32x32x16_f16 v[48:63], v[196:199], v[84:87], v[48:63]
	ds_read_b128 v[196:199], v163 offset:22592
	s_waitcnt lgkmcnt(0)
	v_mfma_f32_32x32x16_f16 v[64:79], v[196:199], v[88:91], v[64:79]
	ds_read_b128 v[196:199], v163 offset:29248
	s_waitcnt lgkmcnt(0)
	v_mfma_f32_32x32x16_f16 v[48:63], v[196:199], v[88:91], v[48:63]
	ds_read_b128 v[196:199], v163 offset:22624
	s_waitcnt lgkmcnt(0)
	v_mfma_f32_32x32x16_f16 v[64:79], v[196:199], v[92:95], v[64:79]
	v_add_f32_e32 v196, v201, v200
	v_add_f32_e32 v5, v5, v196
	v_add_f32_e32 v5, v6, v5
	v_add_f32_e32 v6, v187, v186
	v_add_f32_e32 v5, v6, v5
	v_add_f32_e32 v6, v13, v9
	v_add_f32_e32 v5, v6, v5
	v_add_f32_e32 v6, v190, v188
	v_add_f32_e32 v5, v6, v5
	ds_read_b128 v[6:9], v163 offset:29312
	v_mfma_f32_32x32x16_f16 v[48:63], v[192:195], v[92:95], v[48:63]
	ds_read_b128 v[196:199], v163 offset:22656
	v_add_f32_e32 v13, v191, v189
	v_add_f32_e32 v5, v13, v5
	v_add_f32_e32 v13, v183, v180
	v_add_f32_e32 v5, v13, v5
	v_add_f32_e32 v13, v184, v181
	v_add_f32_e32 v5, v13, v5
	v_add_f32_e32 v13, v185, v182
	ds_read_b128 v[180:183], v163 offset:29344
	s_waitcnt lgkmcnt(2)
	v_mfma_f32_32x32x16_f16 v[48:63], v[6:9], v[96:99], v[48:63]
	v_add_f32_e32 v5, v13, v5
	v_add_f32_e32 v6, v14, v10
	v_add_f32_e32 v5, v6, v5
	v_add_f32_e32 v6, v15, v11
	v_add_f32_e32 v5, v6, v5
	ds_read_b128 v[6:9], v163 offset:22688
	v_add_f32_e32 v10, v179, v12
	s_waitcnt lgkmcnt(2)
	v_mfma_f32_32x32x16_f16 v[64:79], v[196:199], v[96:99], v[64:79]
	v_add_f32_e32 v5, v10, v5
	v_add_f32_e32 v0, v0, v5
	v_add_f32_e32 v0, v2, v0
	v_add_f32_e32 v0, v153, v0
	s_waitcnt lgkmcnt(1)
	v_mfma_f32_32x32x16_f16 v[48:63], v[180:183], v[100:103], v[48:63]
	s_waitcnt lgkmcnt(0)
	v_mfma_f32_32x32x16_f16 v[64:79], v[6:9], v[100:103], v[64:79]
	s_cmp_ge_u32 s10, s8
	s_cbranch_scc1 .Lma_b1_done
	s_waitcnt vmcnt(5)
	ds_write_b128 v147, v[104:107]
	ds_write_b128 v149, v[108:111]
	ds_write_b128 v151, v[112:115]
	ds_write_b128 v162, v[116:119] offset:13312
	ds_write_b128 v164, v[120:123] offset:13312
; template <int DK, bool MLA>
; DI void attn_item(const h16* __restrict__ Q, const h16* __restrict__ Kp, const h16* __restrict__ Kr, const h16* __restrict__ Vt,
;                   int kbeg, int kend, h16* __restrict__ out, h16* sm) {
;     ...
;     float mx = fmaxf(st[0][0], st[1][0]);
; #pragma unroll
;     for (int i = 1; i < 16; ++i) mx = fmaxf(mx, fmaxf(st[0][i], st[1][i]));
;     mx = x32_max(mx);
;     if (__builtin_amdgcn_ballot_w64(mx > 8.f) != 0) {
;       const float dlt = fmaxf(mx, 0.f);
;       const float alpha = __builtin_amdgcn_exp2f(-dlt);
;       m += dlt;
;       lsum *= alpha;
; #pragma unroll
;       for (int i = 0; i < 16; ++i) { ot[0][i] *= alpha; ot[1][i] *= alpha; st[0][i] -= dlt; st[1][i] -= dlt; }
;     }
.Lma_b1_done:
	s_nop 9
	v_max3_f32 v2, v48, v49, v50
	v_max3_f32 v3, v51, v52, v53
	v_max3_f32 v4, v54, v55, v56
	v_max3_f32 v5, v57, v58, v59
	v_max3_f32 v2, v2, v60, v61
	v_max3_f32 v3, v3, v62, v63
	v_max3_f32 v4, v4, v64, v65
	v_max3_f32 v5, v5, v66, v67
	v_max3_f32 v2, v2, v68, v69
	v_max3_f32 v3, v3, v70, v71
	v_max3_f32 v4, v4, v72, v73
	v_max3_f32 v5, v5, v74, v75
	v_max3_f32 v2, v2, v76, v77
	v_max3_f32 v3, v3, v78, v79
	v_max3_f32 v2, v2, v3, v4
	v_max_f32_e32 v2, v2, v5
	v_mov_b32_e32 v3, v2
	s_nop 1
	v_permlane32_swap_b32_e32 v2, v3
	v_max_f32_e32 v2, v2, v3
	v_cmp_lt_f32_e32 vcc, s79, v2
	s_cbranch_vccz .LBB0_2770
	v_max_f32_e32 v2, v2, v2
	v_max_f32_e32 v2, 0, v2
	v_exp_f32_e64 v4, -v2
	v_add_f32_e32 v178, v178, v2
	v_xor_b32_e32 v204, 0x80000000, v178
	v_mov_b32_e32 v205, v204
	v_mov_b32_e32 v206, v204
	v_mov_b32_e32 v207, v204
	v_mov_b32_e32 v208, v204
	v_mov_b32_e32 v209, v204
	v_mov_b32_e32 v210, v204
	v_mov_b32_e32 v211, v204
	v_mov_b32_e32 v212, v204
	v_mov_b32_e32 v213, v204
	v_mov_b32_e32 v214, v204
	v_mov_b32_e32 v215, v204
	v_mov_b32_e32 v216, v204
	v_mov_b32_e32 v217, v204
	v_mov_b32_e32 v218, v204
	v_mov_b32_e32 v219, v204
	v_pk_add_f32 v[64:65], v[64:65], v[2:3] op_sel_hi:[1,0] neg_lo:[0,1] neg_hi:[0,1]
	v_pk_add_f32 v[48:49], v[48:49], v[2:3] op_sel_hi:[1,0] neg_lo:[0,1] neg_hi:[0,1]
	v_mul_f32_e32 v0, v0, v4
	v_pk_add_f32 v[66:67], v[66:67], v[2:3] op_sel_hi:[1,0] neg_lo:[0,1] neg_hi:[0,1]
	v_pk_add_f32 v[50:51], v[50:51], v[2:3] op_sel_hi:[1,0] neg_lo:[0,1] neg_hi:[0,1]
	v_pk_add_f32 v[68:69], v[68:69], v[2:3] op_sel_hi:[1,0] neg_lo:[0,1] neg_hi:[0,1]
	v_pk_add_f32 v[52:53], v[52:53], v[2:3] op_sel_hi:[1,0] neg_lo:[0,1] neg_hi:[0,1]
	v_pk_add_f32 v[70:71], v[70:71], v[2:3] op_sel_hi:[1,0] neg_lo:[0,1] neg_hi:[0,1]
	v_pk_add_f32 v[54:55], v[54:55], v[2:3] op_sel_hi:[1,0] neg_lo:[0,1] neg_hi:[0,1]
	v_pk_add_f32 v[72:73], v[72:73], v[2:3] op_sel_hi:[1,0] neg_lo:[0,1] neg_hi:[0,1]
	v_pk_add_f32 v[56:57], v[56:57], v[2:3] op_sel_hi:[1,0] neg_lo:[0,1] neg_hi:[0,1]
	v_pk_add_f32 v[74:75], v[74:75], v[2:3] op_sel_hi:[1,0] neg_lo:[0,1] neg_hi:[0,1]
	v_pk_add_f32 v[58:59], v[58:59], v[2:3] op_sel_hi:[1,0] neg_lo:[0,1] neg_hi:[0,1]
	v_pk_add_f32 v[76:77], v[76:77], v[2:3] op_sel_hi:[1,0] neg_lo:[0,1] neg_hi:[0,1]
	v_pk_add_f32 v[60:61], v[60:61], v[2:3] op_sel_hi:[1,0] neg_lo:[0,1] neg_hi:[0,1]
	v_pk_mul_f32 v[46:47], v[46:47], v[4:5] op_sel_hi:[1,0]
	v_pk_mul_f32 v[44:45], v[44:45], v[4:5] op_sel_hi:[1,0]
	v_pk_mul_f32 v[42:43], v[42:43], v[4:5] op_sel_hi:[1,0]
	v_pk_mul_f32 v[40:41], v[40:41], v[4:5] op_sel_hi:[1,0]
	v_pk_mul_f32 v[38:39], v[38:39], v[4:5] op_sel_hi:[1,0]
	v_pk_mul_f32 v[36:37], v[36:37], v[4:5] op_sel_hi:[1,0]
	v_pk_mul_f32 v[34:35], v[34:35], v[4:5] op_sel_hi:[1,0]
	v_pk_mul_f32 v[32:33], v[32:33], v[4:5] op_sel_hi:[1,0]
	v_pk_mul_f32 v[30:31], v[30:31], v[4:5] op_sel_hi:[1,0]
	v_pk_mul_f32 v[28:29], v[28:29], v[4:5] op_sel_hi:[1,0]
	v_pk_mul_f32 v[26:27], v[26:27], v[4:5] op_sel_hi:[1,0]
	v_pk_mul_f32 v[24:25], v[24:25], v[4:5] op_sel_hi:[1,0]
	v_pk_mul_f32 v[22:23], v[22:23], v[4:5] op_sel_hi:[1,0]
	v_pk_mul_f32 v[20:21], v[20:21], v[4:5] op_sel_hi:[1,0]
	v_pk_mul_f32 v[18:19], v[18:19], v[4:5] op_sel_hi:[1,0]
	v_pk_mul_f32 v[16:17], v[16:17], v[4:5] op_sel_hi:[1,0]
	v_pk_add_f32 v[78:79], v[78:79], v[2:3] op_sel_hi:[1,0] neg_lo:[0,1] neg_hi:[0,1]
	v_pk_add_f32 v[62:63], v[62:63], v[2:3] op_sel_hi:[1,0] neg_lo:[0,1] neg_hi:[0,1]
	s_branch .LBB0_2770
